# rmsnorm sample rows spread over all 256 workgroups (waves 0-3 of each) instead of the first 128 workgroups only
# baseline (speedup 1.0000x reference)
.LBB0_632:
	s_cmpk_lg_i32 s26, 0x100
	s_cbranch_scc1 .Lsrow_r1_orig
	s_add_i32 s93, s52, 0xffffe000
	s_and_b32 s97, s93, 7
	s_cmp_gt_u32 s97, 3
	s_cbranch_scc1 .LBB0_662
	s_lshr_b32 s93, s93, 3
	s_lshl_b32 s93, s93, 2
	s_add_i32 s93, s93, s97
	s_add_i32 s32, s93, 0x2000
	s_waitcnt lgkmcnt(0)
	v_and_b32_e32 v195, 63, v164
	v_lshlrev_b32_e32 v162, 4, v195
	v_lshlrev_b32_e32 v163, 5, v195
	v_lshlrev_b32_e32 v243, 2, v195
	v_add_u32_e32 v194, 0x1000, v163
	s_lshl_b32 s97, s93, 12
	s_add_u32 s98, s34, s97
	s_addc_u32 s99, s35, 0
	s_add_u32 s98, s98, 0x19600000
	s_addc_u32 s99, s99, 0
	s_waitcnt lgkmcnt(0)
	s_lshl_b32 s97, s93, 13
	s_add_u32 s94, s10, s97
	s_addc_u32 s95, s11, 0
	global_load_dwordx4 v[118:121], v163, s[94:95]
	global_load_dwordx4 v[122:125], v163, s[94:95] offset:16
	global_load_dwordx4 v[126:129], v163, s[94:95] offset:2048
	global_load_dwordx4 v[130:133], v163, s[94:95] offset:2064
	global_load_dwordx4 v[134:137], v194, s[94:95]
	global_load_dwordx4 v[138:141], v194, s[94:95] offset:16
	global_load_dwordx4 v[142:145], v194, s[94:95] offset:2048
	global_load_dwordx4 v[146:149], v194, s[94:95] offset:2064
	global_load_dwordx4 v[150:153], v162, s[98:99]
	global_load_dwordx4 v[154:157], v162, s[98:99] offset:1024
	global_load_dwordx4 v[158:161], v162, s[98:99] offset:2048
	global_load_dwordx4 v[166:169], v162, s[98:99] offset:3072
	s_add_u32 s98, s98, 0x400000
	s_addc_u32 s99, s99, 0
	global_load_dwordx4 v[170:173], v162, s[98:99]
	global_load_dwordx4 v[174:177], v162, s[98:99] offset:1024
	global_load_dwordx4 v[178:181], v162, s[98:99] offset:2048
	global_load_dwordx4 v[182:185], v162, s[98:99] offset:3072
	s_add_u32 s98, s98, 0x400000
	s_addc_u32 s99, s99, 0
	global_load_dwordx4 v[186:189], v162, s[98:99]
	global_load_dwordx4 v[190:193], v162, s[98:99] offset:1024
	global_load_dwordx4 v[198:201], v162, s[98:99] offset:2048
	global_load_dwordx4 v[202:205], v162, s[98:99] offset:3072
	s_add_u32 s98, s98, 0x400000
	s_addc_u32 s99, s99, 0
	global_load_dwordx4 v[206:209], v162, s[98:99]
	global_load_dwordx4 v[210:213], v162, s[98:99] offset:1024
	global_load_dwordx4 v[214:217], v162, s[98:99] offset:2048
	global_load_dwordx4 v[218:221], v162, s[98:99] offset:3072
	s_add_u32 s98, s98, 0x400000
	s_addc_u32 s99, s99, 0
	s_waitcnt vmcnt(12)
	v_lshlrev_b32_e32 v195, 16, v150
	v_and_b32_e32 v197, 0xffff0000, v150
	v_add_f32_e32 v118, v118, v195
	v_add_f32_e32 v119, v119, v197
	v_lshlrev_b32_e32 v195, 16, v151
	v_and_b32_e32 v197, 0xffff0000, v151
	v_add_f32_e32 v120, v120, v195
	v_add_f32_e32 v121, v121, v197
	v_lshlrev_b32_e32 v195, 16, v152
	v_and_b32_e32 v197, 0xffff0000, v152
	v_add_f32_e32 v122, v122, v195
	v_add_f32_e32 v123, v123, v197
	v_lshlrev_b32_e32 v195, 16, v153
	v_and_b32_e32 v197, 0xffff0000, v153
	v_add_f32_e32 v124, v124, v195
	v_add_f32_e32 v125, v125, v197
	v_lshlrev_b32_e32 v195, 16, v154
	v_and_b32_e32 v197, 0xffff0000, v154
	v_add_f32_e32 v126, v126, v195
	v_add_f32_e32 v127, v127, v197
	v_lshlrev_b32_e32 v195, 16, v155
	v_and_b32_e32 v197, 0xffff0000, v155
	v_add_f32_e32 v128, v128, v195
	v_add_f32_e32 v129, v129, v197
	v_lshlrev_b32_e32 v195, 16, v156
	v_and_b32_e32 v197, 0xffff0000, v156
	v_add_f32_e32 v130, v130, v195
	v_add_f32_e32 v131, v131, v197
	v_lshlrev_b32_e32 v195, 16, v157
	v_and_b32_e32 v197, 0xffff0000, v157
	v_add_f32_e32 v132, v132, v195
	v_add_f32_e32 v133, v133, v197
	v_lshlrev_b32_e32 v195, 16, v158
	v_and_b32_e32 v197, 0xffff0000, v158
	v_add_f32_e32 v134, v134, v195
	v_add_f32_e32 v135, v135, v197
	v_lshlrev_b32_e32 v195, 16, v159
	v_and_b32_e32 v197, 0xffff0000, v159
	v_add_f32_e32 v136, v136, v195
	v_add_f32_e32 v137, v137, v197
	v_lshlrev_b32_e32 v195, 16, v160
	v_and_b32_e32 v197, 0xffff0000, v160
	v_add_f32_e32 v138, v138, v195
	v_add_f32_e32 v139, v139, v197
	v_lshlrev_b32_e32 v195, 16, v161
	v_and_b32_e32 v197, 0xffff0000, v161
	v_add_f32_e32 v140, v140, v195
	v_add_f32_e32 v141, v141, v197
	v_lshlrev_b32_e32 v195, 16, v166
	v_and_b32_e32 v197, 0xffff0000, v166
	v_add_f32_e32 v142, v142, v195
	v_add_f32_e32 v143, v143, v197
	v_lshlrev_b32_e32 v195, 16, v167
	v_and_b32_e32 v197, 0xffff0000, v167
	v_add_f32_e32 v144, v144, v195
	v_add_f32_e32 v145, v145, v197
	v_lshlrev_b32_e32 v195, 16, v168
	v_and_b32_e32 v197, 0xffff0000, v168
	v_add_f32_e32 v146, v146, v195
	v_add_f32_e32 v147, v147, v197
	v_lshlrev_b32_e32 v195, 16, v169
	v_and_b32_e32 v197, 0xffff0000, v169
	v_add_f32_e32 v148, v148, v195
	v_add_f32_e32 v149, v149, v197
	global_load_dwordx4 v[150:153], v162, s[98:99]
	global_load_dwordx4 v[154:157], v162, s[98:99] offset:1024
	global_load_dwordx4 v[158:161], v162, s[98:99] offset:2048
	global_load_dwordx4 v[166:169], v162, s[98:99] offset:3072
	s_add_u32 s98, s98, 0x400000
	s_addc_u32 s99, s99, 0
	s_waitcnt vmcnt(12)
	v_lshlrev_b32_e32 v195, 16, v170
	v_and_b32_e32 v197, 0xffff0000, v170
	v_add_f32_e32 v118, v118, v195
	v_add_f32_e32 v119, v119, v197
	v_lshlrev_b32_e32 v195, 16, v171
	v_and_b32_e32 v197, 0xffff0000, v171
	v_add_f32_e32 v120, v120, v195
	v_add_f32_e32 v121, v121, v197
	v_lshlrev_b32_e32 v195, 16, v172
	v_and_b32_e32 v197, 0xffff0000, v172
	v_add_f32_e32 v122, v122, v195
	v_add_f32_e32 v123, v123, v197
	v_lshlrev_b32_e32 v195, 16, v173
	v_and_b32_e32 v197, 0xffff0000, v173
	v_add_f32_e32 v124, v124, v195
	v_add_f32_e32 v125, v125, v197
	v_lshlrev_b32_e32 v195, 16, v174
	v_and_b32_e32 v197, 0xffff0000, v174
	v_add_f32_e32 v126, v126, v195
	v_add_f32_e32 v127, v127, v197
	v_lshlrev_b32_e32 v195, 16, v175
	v_and_b32_e32 v197, 0xffff0000, v175
	v_add_f32_e32 v128, v128, v195
	v_add_f32_e32 v129, v129, v197
	v_lshlrev_b32_e32 v195, 16, v176
	v_and_b32_e32 v197, 0xffff0000, v176
	v_add_f32_e32 v130, v130, v195
	v_add_f32_e32 v131, v131, v197
	v_lshlrev_b32_e32 v195, 16, v177
	v_and_b32_e32 v197, 0xffff0000, v177
	v_add_f32_e32 v132, v132, v195
	v_add_f32_e32 v133, v133, v197
	v_lshlrev_b32_e32 v195, 16, v178
	v_and_b32_e32 v197, 0xffff0000, v178
	v_add_f32_e32 v134, v134, v195
	v_add_f32_e32 v135, v135, v197
	v_lshlrev_b32_e32 v195, 16, v179
	v_and_b32_e32 v197, 0xffff0000, v179
	v_add_f32_e32 v136, v136, v195
	v_add_f32_e32 v137, v137, v197
	v_lshlrev_b32_e32 v195, 16, v180
	v_and_b32_e32 v197, 0xffff0000, v180
	v_add_f32_e32 v138, v138, v195
	v_add_f32_e32 v139, v139, v197
	v_lshlrev_b32_e32 v195, 16, v181
	v_and_b32_e32 v197, 0xffff0000, v181
	v_add_f32_e32 v140, v140, v195
	v_add_f32_e32 v141, v141, v197
	v_lshlrev_b32_e32 v195, 16, v182
	v_and_b32_e32 v197, 0xffff0000, v182
	v_add_f32_e32 v142, v142, v195
	v_add_f32_e32 v143, v143, v197
	v_lshlrev_b32_e32 v195, 16, v183
	v_and_b32_e32 v197, 0xffff0000, v183
	v_add_f32_e32 v144, v144, v195
	v_add_f32_e32 v145, v145, v197
	v_lshlrev_b32_e32 v195, 16, v184
	v_and_b32_e32 v197, 0xffff0000, v184
	v_add_f32_e32 v146, v146, v195
	v_add_f32_e32 v147, v147, v197
	v_lshlrev_b32_e32 v195, 16, v185
	v_and_b32_e32 v197, 0xffff0000, v185
	v_add_f32_e32 v148, v148, v195
	v_add_f32_e32 v149, v149, v197
	global_load_dwordx4 v[170:173], v162, s[98:99]
	global_load_dwordx4 v[174:177], v162, s[98:99] offset:1024
	global_load_dwordx4 v[178:181], v162, s[98:99] offset:2048
	global_load_dwordx4 v[182:185], v162, s[98:99] offset:3072
	s_add_u32 s98, s98, 0x400000
	s_addc_u32 s99, s99, 0
	s_waitcnt vmcnt(12)
	v_lshlrev_b32_e32 v195, 16, v186
	v_and_b32_e32 v197, 0xffff0000, v186
	v_add_f32_e32 v118, v118, v195
	v_add_f32_e32 v119, v119, v197
	v_lshlrev_b32_e32 v195, 16, v187
	v_and_b32_e32 v197, 0xffff0000, v187
	v_add_f32_e32 v120, v120, v195
	v_add_f32_e32 v121, v121, v197
	v_lshlrev_b32_e32 v195, 16, v188
	v_and_b32_e32 v197, 0xffff0000, v188
	v_add_f32_e32 v122, v122, v195
	v_add_f32_e32 v123, v123, v197
	v_lshlrev_b32_e32 v195, 16, v189
	v_and_b32_e32 v197, 0xffff0000, v189
	v_add_f32_e32 v124, v124, v195
	v_add_f32_e32 v125, v125, v197
	v_lshlrev_b32_e32 v195, 16, v190
	v_and_b32_e32 v197, 0xffff0000, v190
	v_add_f32_e32 v126, v126, v195
	v_add_f32_e32 v127, v127, v197
	v_lshlrev_b32_e32 v195, 16, v191
	v_and_b32_e32 v197, 0xffff0000, v191
	v_add_f32_e32 v128, v128, v195
	v_add_f32_e32 v129, v129, v197
	v_lshlrev_b32_e32 v195, 16, v192
	v_and_b32_e32 v197, 0xffff0000, v192
	v_add_f32_e32 v130, v130, v195
	v_add_f32_e32 v131, v131, v197
	v_lshlrev_b32_e32 v195, 16, v193
	v_and_b32_e32 v197, 0xffff0000, v193
	v_add_f32_e32 v132, v132, v195
	v_add_f32_e32 v133, v133, v197
	v_lshlrev_b32_e32 v195, 16, v198
	v_and_b32_e32 v197, 0xffff0000, v198
	v_add_f32_e32 v134, v134, v195
	v_add_f32_e32 v135, v135, v197
	v_lshlrev_b32_e32 v195, 16, v199
	v_and_b32_e32 v197, 0xffff0000, v199
	v_add_f32_e32 v136, v136, v195
	v_add_f32_e32 v137, v137, v197
	v_lshlrev_b32_e32 v195, 16, v200
	v_and_b32_e32 v197, 0xffff0000, v200
	v_add_f32_e32 v138, v138, v195
	v_add_f32_e32 v139, v139, v197
	v_lshlrev_b32_e32 v195, 16, v201
	v_and_b32_e32 v197, 0xffff0000, v201
	v_add_f32_e32 v140, v140, v195
	v_add_f32_e32 v141, v141, v197
	v_lshlrev_b32_e32 v195, 16, v202
	v_and_b32_e32 v197, 0xffff0000, v202
	v_add_f32_e32 v142, v142, v195
	v_add_f32_e32 v143, v143, v197
	v_lshlrev_b32_e32 v195, 16, v203
	v_and_b32_e32 v197, 0xffff0000, v203
	v_add_f32_e32 v144, v144, v195
	v_add_f32_e32 v145, v145, v197
	v_lshlrev_b32_e32 v195, 16, v204
	v_and_b32_e32 v197, 0xffff0000, v204
	v_add_f32_e32 v146, v146, v195
	v_add_f32_e32 v147, v147, v197
	v_lshlrev_b32_e32 v195, 16, v205
	v_and_b32_e32 v197, 0xffff0000, v205
	v_add_f32_e32 v148, v148, v195
	v_add_f32_e32 v149, v149, v197
	global_load_dwordx4 v[186:189], v162, s[98:99]
	global_load_dwordx4 v[190:193], v162, s[98:99] offset:1024
	global_load_dwordx4 v[198:201], v162, s[98:99] offset:2048
	global_load_dwordx4 v[202:205], v162, s[98:99] offset:3072
	s_add_u32 s98, s98, 0x400000
	s_addc_u32 s99, s99, 0
	s_waitcnt vmcnt(12)
	v_lshlrev_b32_e32 v195, 16, v206
	v_and_b32_e32 v197, 0xffff0000, v206
	v_add_f32_e32 v118, v118, v195
	v_add_f32_e32 v119, v119, v197
	v_lshlrev_b32_e32 v195, 16, v207
	v_and_b32_e32 v197, 0xffff0000, v207
	v_add_f32_e32 v120, v120, v195
	v_add_f32_e32 v121, v121, v197
	v_lshlrev_b32_e32 v195, 16, v208
	v_and_b32_e32 v197, 0xffff0000, v208
	v_add_f32_e32 v122, v122, v195
	v_add_f32_e32 v123, v123, v197
	v_lshlrev_b32_e32 v195, 16, v209
	v_and_b32_e32 v197, 0xffff0000, v209
	v_add_f32_e32 v124, v124, v195
	v_add_f32_e32 v125, v125, v197
	v_lshlrev_b32_e32 v195, 16, v210
	v_and_b32_e32 v197, 0xffff0000, v210
	v_add_f32_e32 v126, v126, v195
	v_add_f32_e32 v127, v127, v197
	v_lshlrev_b32_e32 v195, 16, v211
	v_and_b32_e32 v197, 0xffff0000, v211
	v_add_f32_e32 v128, v128, v195
	v_add_f32_e32 v129, v129, v197
	v_lshlrev_b32_e32 v195, 16, v212
	v_and_b32_e32 v197, 0xffff0000, v212
	v_add_f32_e32 v130, v130, v195
	v_add_f32_e32 v131, v131, v197
	v_lshlrev_b32_e32 v195, 16, v213
	v_and_b32_e32 v197, 0xffff0000, v213
	v_add_f32_e32 v132, v132, v195
	v_add_f32_e32 v133, v133, v197
	v_lshlrev_b32_e32 v195, 16, v214
	v_and_b32_e32 v197, 0xffff0000, v214
	v_add_f32_e32 v134, v134, v195
	v_add_f32_e32 v135, v135, v197
	v_lshlrev_b32_e32 v195, 16, v215
	v_and_b32_e32 v197, 0xffff0000, v215
	v_add_f32_e32 v136, v136, v195
	v_add_f32_e32 v137, v137, v197
	v_lshlrev_b32_e32 v195, 16, v216
	v_and_b32_e32 v197, 0xffff0000, v216
	v_add_f32_e32 v138, v138, v195
	v_add_f32_e32 v139, v139, v197
	v_lshlrev_b32_e32 v195, 16, v217
	v_and_b32_e32 v197, 0xffff0000, v217
	v_add_f32_e32 v140, v140, v195
	v_add_f32_e32 v141, v141, v197
	v_lshlrev_b32_e32 v195, 16, v218
	v_and_b32_e32 v197, 0xffff0000, v218
	v_add_f32_e32 v142, v142, v195
	v_add_f32_e32 v143, v143, v197
	v_lshlrev_b32_e32 v195, 16, v219
	v_and_b32_e32 v197, 0xffff0000, v219
	v_add_f32_e32 v144, v144, v195
	v_add_f32_e32 v145, v145, v197
	v_lshlrev_b32_e32 v195, 16, v220
	v_and_b32_e32 v197, 0xffff0000, v220
	v_add_f32_e32 v146, v146, v195
	v_add_f32_e32 v147, v147, v197
	v_lshlrev_b32_e32 v195, 16, v221
	v_and_b32_e32 v197, 0xffff0000, v221
	v_add_f32_e32 v148, v148, v195
	v_add_f32_e32 v149, v149, v197
	global_load_dwordx4 v[206:209], v162, s[98:99]
	global_load_dwordx4 v[210:213], v162, s[98:99] offset:1024
	global_load_dwordx4 v[214:217], v162, s[98:99] offset:2048
	global_load_dwordx4 v[218:221], v162, s[98:99] offset:3072
	s_add_u32 s98, s98, 0x400000
	s_addc_u32 s99, s99, 0
	s_waitcnt vmcnt(12)
	v_lshlrev_b32_e32 v195, 16, v150
	v_and_b32_e32 v197, 0xffff0000, v150
	v_add_f32_e32 v118, v118, v195
	v_add_f32_e32 v119, v119, v197
	v_lshlrev_b32_e32 v195, 16, v151
	v_and_b32_e32 v197, 0xffff0000, v151
	v_add_f32_e32 v120, v120, v195
	v_add_f32_e32 v121, v121, v197
	v_lshlrev_b32_e32 v195, 16, v152
	v_and_b32_e32 v197, 0xffff0000, v152
	v_add_f32_e32 v122, v122, v195
	v_add_f32_e32 v123, v123, v197
	v_lshlrev_b32_e32 v195, 16, v153
	v_and_b32_e32 v197, 0xffff0000, v153
	v_add_f32_e32 v124, v124, v195
	v_add_f32_e32 v125, v125, v197
	v_lshlrev_b32_e32 v195, 16, v154
	v_and_b32_e32 v197, 0xffff0000, v154
	v_add_f32_e32 v126, v126, v195
	v_add_f32_e32 v127, v127, v197
	v_lshlrev_b32_e32 v195, 16, v155
	v_and_b32_e32 v197, 0xffff0000, v155
	v_add_f32_e32 v128, v128, v195
	v_add_f32_e32 v129, v129, v197
	v_lshlrev_b32_e32 v195, 16, v156
	v_and_b32_e32 v197, 0xffff0000, v156
	v_add_f32_e32 v130, v130, v195
	v_add_f32_e32 v131, v131, v197
	v_lshlrev_b32_e32 v195, 16, v157
	v_and_b32_e32 v197, 0xffff0000, v157
	v_add_f32_e32 v132, v132, v195
	v_add_f32_e32 v133, v133, v197
	v_lshlrev_b32_e32 v195, 16, v158
	v_and_b32_e32 v197, 0xffff0000, v158
	v_add_f32_e32 v134, v134, v195
	v_add_f32_e32 v135, v135, v197
	v_lshlrev_b32_e32 v195, 16, v159
	v_and_b32_e32 v197, 0xffff0000, v159
	v_add_f32_e32 v136, v136, v195
	v_add_f32_e32 v137, v137, v197
	v_lshlrev_b32_e32 v195, 16, v160
	v_and_b32_e32 v197, 0xffff0000, v160
	v_add_f32_e32 v138, v138, v195
	v_add_f32_e32 v139, v139, v197
	v_lshlrev_b32_e32 v195, 16, v161
	v_and_b32_e32 v197, 0xffff0000, v161
	v_add_f32_e32 v140, v140, v195
	v_add_f32_e32 v141, v141, v197
	v_lshlrev_b32_e32 v195, 16, v166
	v_and_b32_e32 v197, 0xffff0000, v166
	v_add_f32_e32 v142, v142, v195
	v_add_f32_e32 v143, v143, v197
	v_lshlrev_b32_e32 v195, 16, v167
	v_and_b32_e32 v197, 0xffff0000, v167
	v_add_f32_e32 v144, v144, v195
	v_add_f32_e32 v145, v145, v197
	v_lshlrev_b32_e32 v195, 16, v168
	v_and_b32_e32 v197, 0xffff0000, v168
	v_add_f32_e32 v146, v146, v195
	v_add_f32_e32 v147, v147, v197
	v_lshlrev_b32_e32 v195, 16, v169
	v_and_b32_e32 v197, 0xffff0000, v169
	v_add_f32_e32 v148, v148, v195
	v_add_f32_e32 v149, v149, v197
	global_load_dwordx4 v[150:153], v163, s[14:15]
	global_load_dwordx4 v[154:157], v163, s[14:15] offset:16
	global_load_dwordx4 v[158:161], v163, s[14:15] offset:2048
	global_load_dwordx4 v[166:169], v163, s[14:15] offset:2064
	s_waitcnt vmcnt(12)
	v_lshlrev_b32_e32 v195, 16, v170
	v_and_b32_e32 v197, 0xffff0000, v170
	v_add_f32_e32 v118, v118, v195
	v_add_f32_e32 v119, v119, v197
	v_lshlrev_b32_e32 v195, 16, v171
	v_and_b32_e32 v197, 0xffff0000, v171
	v_add_f32_e32 v120, v120, v195
	v_add_f32_e32 v121, v121, v197
	v_lshlrev_b32_e32 v195, 16, v172
	v_and_b32_e32 v197, 0xffff0000, v172
	v_add_f32_e32 v122, v122, v195
	v_add_f32_e32 v123, v123, v197
	v_lshlrev_b32_e32 v195, 16, v173
	v_and_b32_e32 v197, 0xffff0000, v173
	v_add_f32_e32 v124, v124, v195
	v_add_f32_e32 v125, v125, v197
	v_lshlrev_b32_e32 v195, 16, v174
	v_and_b32_e32 v197, 0xffff0000, v174
	v_add_f32_e32 v126, v126, v195
	v_add_f32_e32 v127, v127, v197
	v_lshlrev_b32_e32 v195, 16, v175
	v_and_b32_e32 v197, 0xffff0000, v175
	v_add_f32_e32 v128, v128, v195
	v_add_f32_e32 v129, v129, v197
	v_lshlrev_b32_e32 v195, 16, v176
	v_and_b32_e32 v197, 0xffff0000, v176
	v_add_f32_e32 v130, v130, v195
	v_add_f32_e32 v131, v131, v197
	v_lshlrev_b32_e32 v195, 16, v177
	v_and_b32_e32 v197, 0xffff0000, v177
	v_add_f32_e32 v132, v132, v195
	v_add_f32_e32 v133, v133, v197
	v_lshlrev_b32_e32 v195, 16, v178
	v_and_b32_e32 v197, 0xffff0000, v178
	v_add_f32_e32 v134, v134, v195
	v_add_f32_e32 v135, v135, v197
	v_lshlrev_b32_e32 v195, 16, v179
	v_and_b32_e32 v197, 0xffff0000, v179
	v_add_f32_e32 v136, v136, v195
	v_add_f32_e32 v137, v137, v197
	v_lshlrev_b32_e32 v195, 16, v180
	v_and_b32_e32 v197, 0xffff0000, v180
	v_add_f32_e32 v138, v138, v195
	v_add_f32_e32 v139, v139, v197
	v_lshlrev_b32_e32 v195, 16, v181
	v_and_b32_e32 v197, 0xffff0000, v181
	v_add_f32_e32 v140, v140, v195
	v_add_f32_e32 v141, v141, v197
	v_lshlrev_b32_e32 v195, 16, v182
	v_and_b32_e32 v197, 0xffff0000, v182
	v_add_f32_e32 v142, v142, v195
	v_add_f32_e32 v143, v143, v197
	v_lshlrev_b32_e32 v195, 16, v183
	v_and_b32_e32 v197, 0xffff0000, v183
	v_add_f32_e32 v144, v144, v195
	v_add_f32_e32 v145, v145, v197
	v_lshlrev_b32_e32 v195, 16, v184
	v_and_b32_e32 v197, 0xffff0000, v184
	v_add_f32_e32 v146, v146, v195
	v_add_f32_e32 v147, v147, v197
	v_lshlrev_b32_e32 v195, 16, v185
	v_and_b32_e32 v197, 0xffff0000, v185
	v_add_f32_e32 v148, v148, v195
	v_add_f32_e32 v149, v149, v197
	global_load_dwordx4 v[170:173], v194, s[14:15]
	global_load_dwordx4 v[174:177], v194, s[14:15] offset:16
	global_load_dwordx4 v[178:181], v194, s[14:15] offset:2048
	global_load_dwordx4 v[182:185], v194, s[14:15] offset:2064
	s_waitcnt vmcnt(12)
	v_lshlrev_b32_e32 v195, 16, v186
	v_and_b32_e32 v197, 0xffff0000, v186
	v_add_f32_e32 v118, v118, v195
	v_add_f32_e32 v119, v119, v197
	v_lshlrev_b32_e32 v195, 16, v187
	v_and_b32_e32 v197, 0xffff0000, v187
	v_add_f32_e32 v120, v120, v195
	v_add_f32_e32 v121, v121, v197
	v_lshlrev_b32_e32 v195, 16, v188
	v_and_b32_e32 v197, 0xffff0000, v188
	v_add_f32_e32 v122, v122, v195
	v_add_f32_e32 v123, v123, v197
	v_lshlrev_b32_e32 v195, 16, v189
	v_and_b32_e32 v197, 0xffff0000, v189
	v_add_f32_e32 v124, v124, v195
	v_add_f32_e32 v125, v125, v197
	v_lshlrev_b32_e32 v195, 16, v190
	v_and_b32_e32 v197, 0xffff0000, v190
	v_add_f32_e32 v126, v126, v195
	v_add_f32_e32 v127, v127, v197
	v_lshlrev_b32_e32 v195, 16, v191
	v_and_b32_e32 v197, 0xffff0000, v191
	v_add_f32_e32 v128, v128, v195
	v_add_f32_e32 v129, v129, v197
	v_lshlrev_b32_e32 v195, 16, v192
	v_and_b32_e32 v197, 0xffff0000, v192
	v_add_f32_e32 v130, v130, v195
	v_add_f32_e32 v131, v131, v197
	v_lshlrev_b32_e32 v195, 16, v193
	v_and_b32_e32 v197, 0xffff0000, v193
	v_add_f32_e32 v132, v132, v195
	v_add_f32_e32 v133, v133, v197
	v_lshlrev_b32_e32 v195, 16, v198
	v_and_b32_e32 v197, 0xffff0000, v198
	v_add_f32_e32 v134, v134, v195
	v_add_f32_e32 v135, v135, v197
	v_lshlrev_b32_e32 v195, 16, v199
	v_and_b32_e32 v197, 0xffff0000, v199
	v_add_f32_e32 v136, v136, v195
	v_add_f32_e32 v137, v137, v197
	v_lshlrev_b32_e32 v195, 16, v200
	v_and_b32_e32 v197, 0xffff0000, v200
	v_add_f32_e32 v138, v138, v195
	v_add_f32_e32 v139, v139, v197
	v_lshlrev_b32_e32 v195, 16, v201
	v_and_b32_e32 v197, 0xffff0000, v201
	v_add_f32_e32 v140, v140, v195
	v_add_f32_e32 v141, v141, v197
	v_lshlrev_b32_e32 v195, 16, v202
	v_and_b32_e32 v197, 0xffff0000, v202
	v_add_f32_e32 v142, v142, v195
	v_add_f32_e32 v143, v143, v197
	v_lshlrev_b32_e32 v195, 16, v203
	v_and_b32_e32 v197, 0xffff0000, v203
	v_add_f32_e32 v144, v144, v195
	v_add_f32_e32 v145, v145, v197
	v_lshlrev_b32_e32 v195, 16, v204
	v_and_b32_e32 v197, 0xffff0000, v204
	v_add_f32_e32 v146, v146, v195
	v_add_f32_e32 v147, v147, v197
	v_lshlrev_b32_e32 v195, 16, v205
	v_and_b32_e32 v197, 0xffff0000, v205
	v_add_f32_e32 v148, v148, v195
	v_add_f32_e32 v149, v149, v197
	s_waitcnt vmcnt(8)
	v_lshlrev_b32_e32 v195, 16, v206
	v_and_b32_e32 v197, 0xffff0000, v206
	v_add_f32_e32 v118, v118, v195
	v_add_f32_e32 v119, v119, v197
	v_lshlrev_b32_e32 v195, 16, v207
	v_and_b32_e32 v197, 0xffff0000, v207
	v_add_f32_e32 v120, v120, v195
	v_add_f32_e32 v121, v121, v197
	v_lshlrev_b32_e32 v195, 16, v208
	v_and_b32_e32 v197, 0xffff0000, v208
	v_add_f32_e32 v122, v122, v195
	v_add_f32_e32 v123, v123, v197
	v_lshlrev_b32_e32 v195, 16, v209
	v_and_b32_e32 v197, 0xffff0000, v209
	v_add_f32_e32 v124, v124, v195
	v_add_f32_e32 v125, v125, v197
	v_lshlrev_b32_e32 v195, 16, v210
	v_and_b32_e32 v197, 0xffff0000, v210
	v_add_f32_e32 v126, v126, v195
	v_add_f32_e32 v127, v127, v197
	v_lshlrev_b32_e32 v195, 16, v211
	v_and_b32_e32 v197, 0xffff0000, v211
	v_add_f32_e32 v128, v128, v195
	v_add_f32_e32 v129, v129, v197
	v_lshlrev_b32_e32 v195, 16, v212
	v_and_b32_e32 v197, 0xffff0000, v212
	v_add_f32_e32 v130, v130, v195
	v_add_f32_e32 v131, v131, v197
	v_lshlrev_b32_e32 v195, 16, v213
	v_and_b32_e32 v197, 0xffff0000, v213
	v_add_f32_e32 v132, v132, v195
	v_add_f32_e32 v133, v133, v197
	v_lshlrev_b32_e32 v195, 16, v214
	v_and_b32_e32 v197, 0xffff0000, v214
	v_add_f32_e32 v134, v134, v195
	v_add_f32_e32 v135, v135, v197
	v_lshlrev_b32_e32 v195, 16, v215
	v_and_b32_e32 v197, 0xffff0000, v215
	v_add_f32_e32 v136, v136, v195
	v_add_f32_e32 v137, v137, v197
	v_lshlrev_b32_e32 v195, 16, v216
	v_and_b32_e32 v197, 0xffff0000, v216
	v_add_f32_e32 v138, v138, v195
	v_add_f32_e32 v139, v139, v197
	v_lshlrev_b32_e32 v195, 16, v217
	v_and_b32_e32 v197, 0xffff0000, v217
	v_add_f32_e32 v140, v140, v195
	v_add_f32_e32 v141, v141, v197
	v_lshlrev_b32_e32 v195, 16, v218
	v_and_b32_e32 v197, 0xffff0000, v218
	v_add_f32_e32 v142, v142, v195
	v_add_f32_e32 v143, v143, v197
	v_lshlrev_b32_e32 v195, 16, v219
	v_and_b32_e32 v197, 0xffff0000, v219
	v_add_f32_e32 v144, v144, v195
	v_add_f32_e32 v145, v145, v197
	v_lshlrev_b32_e32 v195, 16, v220
	v_and_b32_e32 v197, 0xffff0000, v220
	v_add_f32_e32 v146, v146, v195
	v_add_f32_e32 v147, v147, v197
	v_lshlrev_b32_e32 v195, 16, v221
	v_and_b32_e32 v197, 0xffff0000, v221
	v_add_f32_e32 v148, v148, v195
	v_add_f32_e32 v149, v149, v197
	s_lshl_b32 s97, s32, 12
	s_add_u32 s94, s34, s97
	s_addc_u32 s95, s35, 0
	s_add_u32 s94, s94, 0x20200000
	s_addc_u32 s95, s95, 0
	v_cvt_pk_bf16_f32 v186, v118, v119
	v_cvt_pk_bf16_f32 v187, v120, v121
	v_cvt_pk_bf16_f32 v188, v122, v123
	v_cvt_pk_bf16_f32 v189, v124, v125
	global_store_dwordx4 v162, v[186:189], s[94:95]
	v_cvt_pk_bf16_f32 v190, v126, v127
	v_cvt_pk_bf16_f32 v191, v128, v129
	v_cvt_pk_bf16_f32 v192, v130, v131
	v_cvt_pk_bf16_f32 v193, v132, v133
	global_store_dwordx4 v162, v[190:193], s[94:95] offset:1024
	v_cvt_pk_bf16_f32 v198, v134, v135
	v_cvt_pk_bf16_f32 v199, v136, v137
	v_cvt_pk_bf16_f32 v200, v138, v139
	v_cvt_pk_bf16_f32 v201, v140, v141
	global_store_dwordx4 v162, v[198:201], s[94:95] offset:2048
	v_cvt_pk_bf16_f32 v202, v142, v143
	v_cvt_pk_bf16_f32 v203, v144, v145
	v_cvt_pk_bf16_f32 v204, v146, v147
	v_cvt_pk_bf16_f32 v205, v148, v149
	global_store_dwordx4 v162, v[202:205], s[94:95] offset:3072
	v_lshlrev_b32_e32 v118, 16, v186
	v_and_b32_e32 v119, 0xffff0000, v186
	v_lshlrev_b32_e32 v120, 16, v187
	v_and_b32_e32 v121, 0xffff0000, v187
	v_lshlrev_b32_e32 v122, 16, v188
	v_and_b32_e32 v123, 0xffff0000, v188
	v_lshlrev_b32_e32 v124, 16, v189
	v_and_b32_e32 v125, 0xffff0000, v189
	v_lshlrev_b32_e32 v126, 16, v190
	v_and_b32_e32 v127, 0xffff0000, v190
	v_lshlrev_b32_e32 v128, 16, v191
	v_and_b32_e32 v129, 0xffff0000, v191
	v_lshlrev_b32_e32 v130, 16, v192
	v_and_b32_e32 v131, 0xffff0000, v192
	v_lshlrev_b32_e32 v132, 16, v193
	v_and_b32_e32 v133, 0xffff0000, v193
	v_lshlrev_b32_e32 v134, 16, v198
	v_and_b32_e32 v135, 0xffff0000, v198
	v_lshlrev_b32_e32 v136, 16, v199
	v_and_b32_e32 v137, 0xffff0000, v199
	v_lshlrev_b32_e32 v138, 16, v200
	v_and_b32_e32 v139, 0xffff0000, v200
	v_lshlrev_b32_e32 v140, 16, v201
	v_and_b32_e32 v141, 0xffff0000, v201
	v_lshlrev_b32_e32 v142, 16, v202
	v_and_b32_e32 v143, 0xffff0000, v202
	v_lshlrev_b32_e32 v144, 16, v203
	v_and_b32_e32 v145, 0xffff0000, v203
	v_lshlrev_b32_e32 v146, 16, v204
	v_and_b32_e32 v147, 0xffff0000, v204
	v_lshlrev_b32_e32 v148, 16, v205
	v_and_b32_e32 v149, 0xffff0000, v205
	v_mul_f32_e32 v227, v118, v118
	v_fmac_f32_e32 v227, v119, v119
	v_fmac_f32_e32 v227, v120, v120
	v_fmac_f32_e32 v227, v121, v121
	v_fmac_f32_e32 v227, v122, v122
	v_fmac_f32_e32 v227, v123, v123
	v_fmac_f32_e32 v227, v124, v124
	v_fmac_f32_e32 v227, v125, v125
	v_fmac_f32_e32 v227, v126, v126
	v_fmac_f32_e32 v227, v127, v127
	v_fmac_f32_e32 v227, v128, v128
	v_fmac_f32_e32 v227, v129, v129
	v_fmac_f32_e32 v227, v130, v130
	v_fmac_f32_e32 v227, v131, v131
	v_fmac_f32_e32 v227, v132, v132
	v_fmac_f32_e32 v227, v133, v133
	v_fmac_f32_e32 v227, v134, v134
	v_fmac_f32_e32 v227, v135, v135
	v_fmac_f32_e32 v227, v136, v136
	v_fmac_f32_e32 v227, v137, v137
	v_fmac_f32_e32 v227, v138, v138
	v_fmac_f32_e32 v227, v139, v139
	v_fmac_f32_e32 v227, v140, v140
	v_fmac_f32_e32 v227, v141, v141
	v_fmac_f32_e32 v227, v142, v142
	v_fmac_f32_e32 v227, v143, v143
	v_fmac_f32_e32 v227, v144, v144
	v_fmac_f32_e32 v227, v145, v145
	v_fmac_f32_e32 v227, v146, v146
	v_fmac_f32_e32 v227, v147, v147
	v_fmac_f32_e32 v227, v148, v148
	v_fmac_f32_e32 v227, v149, v149
	v_xor_b32_e32 v195, 4, v243
	ds_bpermute_b32 v242, v195, v227
	s_waitcnt lgkmcnt(0)
	v_add_f32_e32 v227, v227, v242
	v_xor_b32_e32 v195, 8, v243
	ds_bpermute_b32 v242, v195, v227
	s_waitcnt lgkmcnt(0)
	v_add_f32_e32 v227, v227, v242
	v_xor_b32_e32 v195, 16, v243
	ds_bpermute_b32 v242, v195, v227
	s_waitcnt lgkmcnt(0)
	v_add_f32_e32 v227, v227, v242
	v_xor_b32_e32 v195, 32, v243
	ds_bpermute_b32 v242, v195, v227
	s_waitcnt lgkmcnt(0)
	v_add_f32_e32 v227, v227, v242
	v_xor_b32_e32 v195, 64, v243
	ds_bpermute_b32 v242, v195, v227
	s_waitcnt lgkmcnt(0)
	v_add_f32_e32 v227, v227, v242
	v_xor_b32_e32 v195, 128, v243
	ds_bpermute_b32 v242, v195, v227
	s_waitcnt lgkmcnt(0)
	v_add_f32_e32 v227, v227, v242
	v_mov_b32_e32 v240, 0x3a000000
	v_mov_b32_e32 v241, 0x358637bd
	v_fma_f32 v227, v227, v240, v241
	v_rsq_f32_e32 v227, v227
	s_lshl_b32 s97, s32, 12
	s_add_u32 s100, s34, s97
	s_addc_u32 s101, s35, 0
	s_add_u32 s100, s100, 0x9800000
	s_addc_u32 s101, s101, 0
	s_waitcnt vmcnt(4)
	v_mul_f32_e32 v118, v118, v227
	v_mul_f32_e32 v118, v118, v150
	v_mul_f32_e32 v119, v119, v227
	v_mul_f32_e32 v119, v119, v151
	v_mul_f32_e32 v120, v120, v227
	v_mul_f32_e32 v120, v120, v152
	v_mul_f32_e32 v121, v121, v227
	v_mul_f32_e32 v121, v121, v153
	v_mul_f32_e32 v122, v122, v227
	v_mul_f32_e32 v122, v122, v154
	v_mul_f32_e32 v123, v123, v227
	v_mul_f32_e32 v123, v123, v155
	v_mul_f32_e32 v124, v124, v227
	v_mul_f32_e32 v124, v124, v156
	v_mul_f32_e32 v125, v125, v227
	v_mul_f32_e32 v125, v125, v157
	v_mul_f32_e32 v126, v126, v227
	v_mul_f32_e32 v126, v126, v158
	v_mul_f32_e32 v127, v127, v227
	v_mul_f32_e32 v127, v127, v159
	v_mul_f32_e32 v128, v128, v227
	v_mul_f32_e32 v128, v128, v160
	v_mul_f32_e32 v129, v129, v227
	v_mul_f32_e32 v129, v129, v161
	v_mul_f32_e32 v130, v130, v227
	v_mul_f32_e32 v130, v130, v166
	v_mul_f32_e32 v131, v131, v227
	v_mul_f32_e32 v131, v131, v167
	v_mul_f32_e32 v132, v132, v227
	v_mul_f32_e32 v132, v132, v168
	v_mul_f32_e32 v133, v133, v227
	v_mul_f32_e32 v133, v133, v169
	v_mul_f32_e32 v134, v134, v227
	v_mul_f32_e32 v134, v134, v170
	v_mul_f32_e32 v135, v135, v227
	v_mul_f32_e32 v135, v135, v171
	v_mul_f32_e32 v136, v136, v227
	v_mul_f32_e32 v136, v136, v172
	v_mul_f32_e32 v137, v137, v227
	v_mul_f32_e32 v137, v137, v173
	v_mul_f32_e32 v138, v138, v227
	v_mul_f32_e32 v138, v138, v174
	v_mul_f32_e32 v139, v139, v227
	v_mul_f32_e32 v139, v139, v175
	v_mul_f32_e32 v140, v140, v227
	v_mul_f32_e32 v140, v140, v176
	v_mul_f32_e32 v141, v141, v227
	v_mul_f32_e32 v141, v141, v177
	v_mul_f32_e32 v142, v142, v227
	v_mul_f32_e32 v142, v142, v178
	v_mul_f32_e32 v143, v143, v227
	v_mul_f32_e32 v143, v143, v179
	v_mul_f32_e32 v144, v144, v227
	v_mul_f32_e32 v144, v144, v180
	v_mul_f32_e32 v145, v145, v227
	v_mul_f32_e32 v145, v145, v181
	v_mul_f32_e32 v146, v146, v227
	v_mul_f32_e32 v146, v146, v182
	v_mul_f32_e32 v147, v147, v227
	v_mul_f32_e32 v147, v147, v183
	v_mul_f32_e32 v148, v148, v227
	v_mul_f32_e32 v148, v148, v184
	v_mul_f32_e32 v149, v149, v227
	v_mul_f32_e32 v149, v149, v185
	v_cvt_pk_bf16_f32 v206, v118, v119
	v_cvt_pk_bf16_f32 v207, v120, v121
	v_cvt_pk_bf16_f32 v208, v122, v123
	v_cvt_pk_bf16_f32 v209, v124, v125
	global_store_dwordx4 v162, v[206:209], s[100:101]
	v_cvt_pk_bf16_f32 v210, v126, v127
	v_cvt_pk_bf16_f32 v211, v128, v129
	v_cvt_pk_bf16_f32 v212, v130, v131
	v_cvt_pk_bf16_f32 v213, v132, v133
	global_store_dwordx4 v162, v[210:213], s[100:101] offset:1024
	v_cvt_pk_bf16_f32 v214, v134, v135
	v_cvt_pk_bf16_f32 v215, v136, v137
	v_cvt_pk_bf16_f32 v216, v138, v139
	v_cvt_pk_bf16_f32 v217, v140, v141
	global_store_dwordx4 v162, v[214:217], s[100:101] offset:2048
	v_cvt_pk_bf16_f32 v218, v142, v143
	v_cvt_pk_bf16_f32 v219, v144, v145
	v_cvt_pk_bf16_f32 v220, v146, v147
	v_cvt_pk_bf16_f32 v221, v148, v149
	global_store_dwordx4 v162, v[218:221], s[100:101] offset:3072
	s_branch .LBB0_662

.LBB0_1028:
	s_cmpk_lg_i32 s26, 0x100
	s_cbranch_scc1 .Lsrow_r2_orig
	s_add_i32 s93, s48, 0xffffe000
	s_and_b32 s97, s93, 7
	s_cmp_gt_u32 s97, 3
	s_cbranch_scc1 .LBB0_1042
	s_lshr_b32 s93, s93, 3
	s_lshl_b32 s93, s93, 2
	s_add_i32 s93, s93, s97
	s_add_i32 s32, s93, 0x2000
	s_waitcnt lgkmcnt(0)
	v_and_b32_e32 v195, 63, v164
	v_lshlrev_b32_e32 v162, 4, v195
	v_lshlrev_b32_e32 v163, 5, v195
	v_lshlrev_b32_e32 v243, 2, v195
	v_add_u32_e32 v194, 0x1000, v163
	s_lshl_b32 s97, s93, 12
	s_add_u32 s98, s34, s97
	s_addc_u32 s99, s35, 0
	s_add_u32 s98, s98, 0x19600000
	s_addc_u32 s99, s99, 0
	s_lshl_b32 s97, s32, 12
	s_add_u32 s94, s34, s97
	s_addc_u32 s95, s35, 0
	s_add_u32 s94, s94, 0x20200000
	s_addc_u32 s95, s95, 0
	global_load_dwordx4 v[222:225], v162, s[94:95]
	global_load_dwordx4 v[228:231], v162, s[94:95] offset:1024
	global_load_dwordx4 v[232:235], v162, s[94:95] offset:2048
	global_load_dwordx4 v[236:239], v162, s[94:95] offset:3072
	global_load_dwordx4 v[150:153], v162, s[98:99]
	global_load_dwordx4 v[154:157], v162, s[98:99] offset:1024
	global_load_dwordx4 v[158:161], v162, s[98:99] offset:2048
	global_load_dwordx4 v[166:169], v162, s[98:99] offset:3072
	s_add_u32 s98, s98, 0x400000
	s_addc_u32 s99, s99, 0
	global_load_dwordx4 v[170:173], v162, s[98:99]
	global_load_dwordx4 v[174:177], v162, s[98:99] offset:1024
	global_load_dwordx4 v[178:181], v162, s[98:99] offset:2048
	global_load_dwordx4 v[182:185], v162, s[98:99] offset:3072
	s_add_u32 s98, s98, 0x400000
	s_addc_u32 s99, s99, 0
	global_load_dwordx4 v[186:189], v162, s[98:99]
	global_load_dwordx4 v[190:193], v162, s[98:99] offset:1024
	global_load_dwordx4 v[198:201], v162, s[98:99] offset:2048
	global_load_dwordx4 v[202:205], v162, s[98:99] offset:3072
	s_add_u32 s98, s98, 0x400000
	s_addc_u32 s99, s99, 0
	global_load_dwordx4 v[206:209], v162, s[98:99]
	global_load_dwordx4 v[210:213], v162, s[98:99] offset:1024
	global_load_dwordx4 v[214:217], v162, s[98:99] offset:2048
	global_load_dwordx4 v[218:221], v162, s[98:99] offset:3072
	s_add_u32 s98, s98, 0x400000
	s_addc_u32 s99, s99, 0
	s_waitcnt vmcnt(16)
	v_lshlrev_b32_e32 v118, 16, v222
	v_and_b32_e32 v119, 0xffff0000, v222
	v_lshlrev_b32_e32 v120, 16, v223
	v_and_b32_e32 v121, 0xffff0000, v223
	v_lshlrev_b32_e32 v122, 16, v224
	v_and_b32_e32 v123, 0xffff0000, v224
	v_lshlrev_b32_e32 v124, 16, v225
	v_and_b32_e32 v125, 0xffff0000, v225
	v_lshlrev_b32_e32 v126, 16, v228
	v_and_b32_e32 v127, 0xffff0000, v228
	v_lshlrev_b32_e32 v128, 16, v229
	v_and_b32_e32 v129, 0xffff0000, v229
	v_lshlrev_b32_e32 v130, 16, v230
	v_and_b32_e32 v131, 0xffff0000, v230
	v_lshlrev_b32_e32 v132, 16, v231
	v_and_b32_e32 v133, 0xffff0000, v231
	v_lshlrev_b32_e32 v134, 16, v232
	v_and_b32_e32 v135, 0xffff0000, v232
	v_lshlrev_b32_e32 v136, 16, v233
	v_and_b32_e32 v137, 0xffff0000, v233
	v_lshlrev_b32_e32 v138, 16, v234
	v_and_b32_e32 v139, 0xffff0000, v234
	v_lshlrev_b32_e32 v140, 16, v235
	v_and_b32_e32 v141, 0xffff0000, v235
	v_lshlrev_b32_e32 v142, 16, v236
	v_and_b32_e32 v143, 0xffff0000, v236
	v_lshlrev_b32_e32 v144, 16, v237
	v_and_b32_e32 v145, 0xffff0000, v237
	v_lshlrev_b32_e32 v146, 16, v238
	v_and_b32_e32 v147, 0xffff0000, v238
	v_lshlrev_b32_e32 v148, 16, v239
	v_and_b32_e32 v149, 0xffff0000, v239
	s_waitcnt vmcnt(12)
	v_lshlrev_b32_e32 v195, 16, v150
	v_and_b32_e32 v197, 0xffff0000, v150
	v_add_f32_e32 v118, v118, v195
	v_add_f32_e32 v119, v119, v197
	v_lshlrev_b32_e32 v195, 16, v151
	v_and_b32_e32 v197, 0xffff0000, v151
	v_add_f32_e32 v120, v120, v195
	v_add_f32_e32 v121, v121, v197
	v_lshlrev_b32_e32 v195, 16, v152
	v_and_b32_e32 v197, 0xffff0000, v152
	v_add_f32_e32 v122, v122, v195
	v_add_f32_e32 v123, v123, v197
	v_lshlrev_b32_e32 v195, 16, v153
	v_and_b32_e32 v197, 0xffff0000, v153
	v_add_f32_e32 v124, v124, v195
	v_add_f32_e32 v125, v125, v197
	v_lshlrev_b32_e32 v195, 16, v154
	v_and_b32_e32 v197, 0xffff0000, v154
	v_add_f32_e32 v126, v126, v195
	v_add_f32_e32 v127, v127, v197
	v_lshlrev_b32_e32 v195, 16, v155
	v_and_b32_e32 v197, 0xffff0000, v155
	v_add_f32_e32 v128, v128, v195
	v_add_f32_e32 v129, v129, v197
	v_lshlrev_b32_e32 v195, 16, v156
	v_and_b32_e32 v197, 0xffff0000, v156
	v_add_f32_e32 v130, v130, v195
	v_add_f32_e32 v131, v131, v197
	v_lshlrev_b32_e32 v195, 16, v157
	v_and_b32_e32 v197, 0xffff0000, v157
	v_add_f32_e32 v132, v132, v195
	v_add_f32_e32 v133, v133, v197
	v_lshlrev_b32_e32 v195, 16, v158
	v_and_b32_e32 v197, 0xffff0000, v158
	v_add_f32_e32 v134, v134, v195
	v_add_f32_e32 v135, v135, v197
	v_lshlrev_b32_e32 v195, 16, v159
	v_and_b32_e32 v197, 0xffff0000, v159
	v_add_f32_e32 v136, v136, v195
	v_add_f32_e32 v137, v137, v197
	v_lshlrev_b32_e32 v195, 16, v160
	v_and_b32_e32 v197, 0xffff0000, v160
	v_add_f32_e32 v138, v138, v195
	v_add_f32_e32 v139, v139, v197
	v_lshlrev_b32_e32 v195, 16, v161
	v_and_b32_e32 v197, 0xffff0000, v161
	v_add_f32_e32 v140, v140, v195
	v_add_f32_e32 v141, v141, v197
	v_lshlrev_b32_e32 v195, 16, v166
	v_and_b32_e32 v197, 0xffff0000, v166
	v_add_f32_e32 v142, v142, v195
	v_add_f32_e32 v143, v143, v197
	v_lshlrev_b32_e32 v195, 16, v167
	v_and_b32_e32 v197, 0xffff0000, v167
	v_add_f32_e32 v144, v144, v195
	v_add_f32_e32 v145, v145, v197
	v_lshlrev_b32_e32 v195, 16, v168
	v_and_b32_e32 v197, 0xffff0000, v168
	v_add_f32_e32 v146, v146, v195
	v_add_f32_e32 v147, v147, v197
	v_lshlrev_b32_e32 v195, 16, v169
	v_and_b32_e32 v197, 0xffff0000, v169
	v_add_f32_e32 v148, v148, v195
	v_add_f32_e32 v149, v149, v197
	global_load_dwordx4 v[150:153], v162, s[98:99]
	global_load_dwordx4 v[154:157], v162, s[98:99] offset:1024
	global_load_dwordx4 v[158:161], v162, s[98:99] offset:2048
	global_load_dwordx4 v[166:169], v162, s[98:99] offset:3072
	s_add_u32 s98, s98, 0x400000
	s_addc_u32 s99, s99, 0
	s_waitcnt vmcnt(12)
	v_lshlrev_b32_e32 v195, 16, v170
	v_and_b32_e32 v197, 0xffff0000, v170
	v_add_f32_e32 v118, v118, v195
	v_add_f32_e32 v119, v119, v197
	v_lshlrev_b32_e32 v195, 16, v171
	v_and_b32_e32 v197, 0xffff0000, v171
	v_add_f32_e32 v120, v120, v195
	v_add_f32_e32 v121, v121, v197
	v_lshlrev_b32_e32 v195, 16, v172
	v_and_b32_e32 v197, 0xffff0000, v172
	v_add_f32_e32 v122, v122, v195
	v_add_f32_e32 v123, v123, v197
	v_lshlrev_b32_e32 v195, 16, v173
	v_and_b32_e32 v197, 0xffff0000, v173
	v_add_f32_e32 v124, v124, v195
	v_add_f32_e32 v125, v125, v197
	v_lshlrev_b32_e32 v195, 16, v174
	v_and_b32_e32 v197, 0xffff0000, v174
	v_add_f32_e32 v126, v126, v195
	v_add_f32_e32 v127, v127, v197
	v_lshlrev_b32_e32 v195, 16, v175
	v_and_b32_e32 v197, 0xffff0000, v175
	v_add_f32_e32 v128, v128, v195
	v_add_f32_e32 v129, v129, v197
	v_lshlrev_b32_e32 v195, 16, v176
	v_and_b32_e32 v197, 0xffff0000, v176
	v_add_f32_e32 v130, v130, v195
	v_add_f32_e32 v131, v131, v197
	v_lshlrev_b32_e32 v195, 16, v177
	v_and_b32_e32 v197, 0xffff0000, v177
	v_add_f32_e32 v132, v132, v195
	v_add_f32_e32 v133, v133, v197
	v_lshlrev_b32_e32 v195, 16, v178
	v_and_b32_e32 v197, 0xffff0000, v178
	v_add_f32_e32 v134, v134, v195
	v_add_f32_e32 v135, v135, v197
	v_lshlrev_b32_e32 v195, 16, v179
	v_and_b32_e32 v197, 0xffff0000, v179
	v_add_f32_e32 v136, v136, v195
	v_add_f32_e32 v137, v137, v197
	v_lshlrev_b32_e32 v195, 16, v180
	v_and_b32_e32 v197, 0xffff0000, v180
	v_add_f32_e32 v138, v138, v195
	v_add_f32_e32 v139, v139, v197
	v_lshlrev_b32_e32 v195, 16, v181
	v_and_b32_e32 v197, 0xffff0000, v181
	v_add_f32_e32 v140, v140, v195
	v_add_f32_e32 v141, v141, v197
	v_lshlrev_b32_e32 v195, 16, v182
	v_and_b32_e32 v197, 0xffff0000, v182
	v_add_f32_e32 v142, v142, v195
	v_add_f32_e32 v143, v143, v197
	v_lshlrev_b32_e32 v195, 16, v183
	v_and_b32_e32 v197, 0xffff0000, v183
	v_add_f32_e32 v144, v144, v195
	v_add_f32_e32 v145, v145, v197
	v_lshlrev_b32_e32 v195, 16, v184
	v_and_b32_e32 v197, 0xffff0000, v184
	v_add_f32_e32 v146, v146, v195
	v_add_f32_e32 v147, v147, v197
	v_lshlrev_b32_e32 v195, 16, v185
	v_and_b32_e32 v197, 0xffff0000, v185
	v_add_f32_e32 v148, v148, v195
	v_add_f32_e32 v149, v149, v197
	global_load_dwordx4 v[170:173], v162, s[98:99]
	global_load_dwordx4 v[174:177], v162, s[98:99] offset:1024
	global_load_dwordx4 v[178:181], v162, s[98:99] offset:2048
	global_load_dwordx4 v[182:185], v162, s[98:99] offset:3072
	s_add_u32 s98, s98, 0x400000
	s_addc_u32 s99, s99, 0
	s_waitcnt vmcnt(12)
	v_lshlrev_b32_e32 v195, 16, v186
	v_and_b32_e32 v197, 0xffff0000, v186
	v_add_f32_e32 v118, v118, v195
	v_add_f32_e32 v119, v119, v197
	v_lshlrev_b32_e32 v195, 16, v187
	v_and_b32_e32 v197, 0xffff0000, v187
	v_add_f32_e32 v120, v120, v195
	v_add_f32_e32 v121, v121, v197
	v_lshlrev_b32_e32 v195, 16, v188
	v_and_b32_e32 v197, 0xffff0000, v188
	v_add_f32_e32 v122, v122, v195
	v_add_f32_e32 v123, v123, v197
	v_lshlrev_b32_e32 v195, 16, v189
	v_and_b32_e32 v197, 0xffff0000, v189
	v_add_f32_e32 v124, v124, v195
	v_add_f32_e32 v125, v125, v197
	v_lshlrev_b32_e32 v195, 16, v190
	v_and_b32_e32 v197, 0xffff0000, v190
	v_add_f32_e32 v126, v126, v195
	v_add_f32_e32 v127, v127, v197
	v_lshlrev_b32_e32 v195, 16, v191
	v_and_b32_e32 v197, 0xffff0000, v191
	v_add_f32_e32 v128, v128, v195
	v_add_f32_e32 v129, v129, v197
	v_lshlrev_b32_e32 v195, 16, v192
	v_and_b32_e32 v197, 0xffff0000, v192
	v_add_f32_e32 v130, v130, v195
	v_add_f32_e32 v131, v131, v197
	v_lshlrev_b32_e32 v195, 16, v193
	v_and_b32_e32 v197, 0xffff0000, v193
	v_add_f32_e32 v132, v132, v195
	v_add_f32_e32 v133, v133, v197
	v_lshlrev_b32_e32 v195, 16, v198
	v_and_b32_e32 v197, 0xffff0000, v198
	v_add_f32_e32 v134, v134, v195
	v_add_f32_e32 v135, v135, v197
	v_lshlrev_b32_e32 v195, 16, v199
	v_and_b32_e32 v197, 0xffff0000, v199
	v_add_f32_e32 v136, v136, v195
	v_add_f32_e32 v137, v137, v197
	v_lshlrev_b32_e32 v195, 16, v200
	v_and_b32_e32 v197, 0xffff0000, v200
	v_add_f32_e32 v138, v138, v195
	v_add_f32_e32 v139, v139, v197
	v_lshlrev_b32_e32 v195, 16, v201
	v_and_b32_e32 v197, 0xffff0000, v201
	v_add_f32_e32 v140, v140, v195
	v_add_f32_e32 v141, v141, v197
	v_lshlrev_b32_e32 v195, 16, v202
	v_and_b32_e32 v197, 0xffff0000, v202
	v_add_f32_e32 v142, v142, v195
	v_add_f32_e32 v143, v143, v197
	v_lshlrev_b32_e32 v195, 16, v203
	v_and_b32_e32 v197, 0xffff0000, v203
	v_add_f32_e32 v144, v144, v195
	v_add_f32_e32 v145, v145, v197
	v_lshlrev_b32_e32 v195, 16, v204
	v_and_b32_e32 v197, 0xffff0000, v204
	v_add_f32_e32 v146, v146, v195
	v_add_f32_e32 v147, v147, v197
	v_lshlrev_b32_e32 v195, 16, v205
	v_and_b32_e32 v197, 0xffff0000, v205
	v_add_f32_e32 v148, v148, v195
	v_add_f32_e32 v149, v149, v197
	global_load_dwordx4 v[186:189], v162, s[98:99]
	global_load_dwordx4 v[190:193], v162, s[98:99] offset:1024
	global_load_dwordx4 v[198:201], v162, s[98:99] offset:2048
	global_load_dwordx4 v[202:205], v162, s[98:99] offset:3072
	s_add_u32 s98, s98, 0x400000
	s_addc_u32 s99, s99, 0
	s_waitcnt vmcnt(12)
	v_lshlrev_b32_e32 v195, 16, v206
	v_and_b32_e32 v197, 0xffff0000, v206
	v_add_f32_e32 v118, v118, v195
	v_add_f32_e32 v119, v119, v197
	v_lshlrev_b32_e32 v195, 16, v207
	v_and_b32_e32 v197, 0xffff0000, v207
	v_add_f32_e32 v120, v120, v195
	v_add_f32_e32 v121, v121, v197
	v_lshlrev_b32_e32 v195, 16, v208
	v_and_b32_e32 v197, 0xffff0000, v208
	v_add_f32_e32 v122, v122, v195
	v_add_f32_e32 v123, v123, v197
	v_lshlrev_b32_e32 v195, 16, v209
	v_and_b32_e32 v197, 0xffff0000, v209
	v_add_f32_e32 v124, v124, v195
	v_add_f32_e32 v125, v125, v197
	v_lshlrev_b32_e32 v195, 16, v210
	v_and_b32_e32 v197, 0xffff0000, v210
	v_add_f32_e32 v126, v126, v195
	v_add_f32_e32 v127, v127, v197
	v_lshlrev_b32_e32 v195, 16, v211
	v_and_b32_e32 v197, 0xffff0000, v211
	v_add_f32_e32 v128, v128, v195
	v_add_f32_e32 v129, v129, v197
	v_lshlrev_b32_e32 v195, 16, v212
	v_and_b32_e32 v197, 0xffff0000, v212
	v_add_f32_e32 v130, v130, v195
	v_add_f32_e32 v131, v131, v197
	v_lshlrev_b32_e32 v195, 16, v213
	v_and_b32_e32 v197, 0xffff0000, v213
	v_add_f32_e32 v132, v132, v195
	v_add_f32_e32 v133, v133, v197
	v_lshlrev_b32_e32 v195, 16, v214
	v_and_b32_e32 v197, 0xffff0000, v214
	v_add_f32_e32 v134, v134, v195
	v_add_f32_e32 v135, v135, v197
	v_lshlrev_b32_e32 v195, 16, v215
	v_and_b32_e32 v197, 0xffff0000, v215
	v_add_f32_e32 v136, v136, v195
	v_add_f32_e32 v137, v137, v197
	v_lshlrev_b32_e32 v195, 16, v216
	v_and_b32_e32 v197, 0xffff0000, v216
	v_add_f32_e32 v138, v138, v195
	v_add_f32_e32 v139, v139, v197
	v_lshlrev_b32_e32 v195, 16, v217
	v_and_b32_e32 v197, 0xffff0000, v217
	v_add_f32_e32 v140, v140, v195
	v_add_f32_e32 v141, v141, v197
	v_lshlrev_b32_e32 v195, 16, v218
	v_and_b32_e32 v197, 0xffff0000, v218
	v_add_f32_e32 v142, v142, v195
	v_add_f32_e32 v143, v143, v197
	v_lshlrev_b32_e32 v195, 16, v219
	v_and_b32_e32 v197, 0xffff0000, v219
	v_add_f32_e32 v144, v144, v195
	v_add_f32_e32 v145, v145, v197
	v_lshlrev_b32_e32 v195, 16, v220
	v_and_b32_e32 v197, 0xffff0000, v220
	v_add_f32_e32 v146, v146, v195
	v_add_f32_e32 v147, v147, v197
	v_lshlrev_b32_e32 v195, 16, v221
	v_and_b32_e32 v197, 0xffff0000, v221
	v_add_f32_e32 v148, v148, v195
	v_add_f32_e32 v149, v149, v197
	global_load_dwordx4 v[206:209], v162, s[98:99]
	global_load_dwordx4 v[210:213], v162, s[98:99] offset:1024
	global_load_dwordx4 v[214:217], v162, s[98:99] offset:2048
	global_load_dwordx4 v[218:221], v162, s[98:99] offset:3072
	s_add_u32 s98, s98, 0x400000
	s_addc_u32 s99, s99, 0
	s_waitcnt vmcnt(12)
	v_lshlrev_b32_e32 v195, 16, v150
	v_and_b32_e32 v197, 0xffff0000, v150
	v_add_f32_e32 v118, v118, v195
	v_add_f32_e32 v119, v119, v197
	v_lshlrev_b32_e32 v195, 16, v151
	v_and_b32_e32 v197, 0xffff0000, v151
	v_add_f32_e32 v120, v120, v195
	v_add_f32_e32 v121, v121, v197
	v_lshlrev_b32_e32 v195, 16, v152
	v_and_b32_e32 v197, 0xffff0000, v152
	v_add_f32_e32 v122, v122, v195
	v_add_f32_e32 v123, v123, v197
	v_lshlrev_b32_e32 v195, 16, v153
	v_and_b32_e32 v197, 0xffff0000, v153
	v_add_f32_e32 v124, v124, v195
	v_add_f32_e32 v125, v125, v197
	v_lshlrev_b32_e32 v195, 16, v154
	v_and_b32_e32 v197, 0xffff0000, v154
	v_add_f32_e32 v126, v126, v195
	v_add_f32_e32 v127, v127, v197
	v_lshlrev_b32_e32 v195, 16, v155
	v_and_b32_e32 v197, 0xffff0000, v155
	v_add_f32_e32 v128, v128, v195
	v_add_f32_e32 v129, v129, v197
	v_lshlrev_b32_e32 v195, 16, v156
	v_and_b32_e32 v197, 0xffff0000, v156
	v_add_f32_e32 v130, v130, v195
	v_add_f32_e32 v131, v131, v197
	v_lshlrev_b32_e32 v195, 16, v157
	v_and_b32_e32 v197, 0xffff0000, v157
	v_add_f32_e32 v132, v132, v195
	v_add_f32_e32 v133, v133, v197
	v_lshlrev_b32_e32 v195, 16, v158
	v_and_b32_e32 v197, 0xffff0000, v158
	v_add_f32_e32 v134, v134, v195
	v_add_f32_e32 v135, v135, v197
	v_lshlrev_b32_e32 v195, 16, v159
	v_and_b32_e32 v197, 0xffff0000, v159
	v_add_f32_e32 v136, v136, v195
	v_add_f32_e32 v137, v137, v197
	v_lshlrev_b32_e32 v195, 16, v160
	v_and_b32_e32 v197, 0xffff0000, v160
	v_add_f32_e32 v138, v138, v195
	v_add_f32_e32 v139, v139, v197
	v_lshlrev_b32_e32 v195, 16, v161
	v_and_b32_e32 v197, 0xffff0000, v161
	v_add_f32_e32 v140, v140, v195
	v_add_f32_e32 v141, v141, v197
	v_lshlrev_b32_e32 v195, 16, v166
	v_and_b32_e32 v197, 0xffff0000, v166
	v_add_f32_e32 v142, v142, v195
	v_add_f32_e32 v143, v143, v197
	v_lshlrev_b32_e32 v195, 16, v167
	v_and_b32_e32 v197, 0xffff0000, v167
	v_add_f32_e32 v144, v144, v195
	v_add_f32_e32 v145, v145, v197
	v_lshlrev_b32_e32 v195, 16, v168
	v_and_b32_e32 v197, 0xffff0000, v168
	v_add_f32_e32 v146, v146, v195
	v_add_f32_e32 v147, v147, v197
	v_lshlrev_b32_e32 v195, 16, v169
	v_and_b32_e32 v197, 0xffff0000, v169
	v_add_f32_e32 v148, v148, v195
	v_add_f32_e32 v149, v149, v197
	global_load_dwordx4 v[150:153], v163, s[12:13]
	global_load_dwordx4 v[154:157], v163, s[12:13] offset:16
	global_load_dwordx4 v[158:161], v163, s[12:13] offset:2048
	global_load_dwordx4 v[166:169], v163, s[12:13] offset:2064
	s_waitcnt vmcnt(12)
	v_lshlrev_b32_e32 v195, 16, v170
	v_and_b32_e32 v197, 0xffff0000, v170
	v_add_f32_e32 v118, v118, v195
	v_add_f32_e32 v119, v119, v197
	v_lshlrev_b32_e32 v195, 16, v171
	v_and_b32_e32 v197, 0xffff0000, v171
	v_add_f32_e32 v120, v120, v195
	v_add_f32_e32 v121, v121, v197
	v_lshlrev_b32_e32 v195, 16, v172
	v_and_b32_e32 v197, 0xffff0000, v172
	v_add_f32_e32 v122, v122, v195
	v_add_f32_e32 v123, v123, v197
	v_lshlrev_b32_e32 v195, 16, v173
	v_and_b32_e32 v197, 0xffff0000, v173
	v_add_f32_e32 v124, v124, v195
	v_add_f32_e32 v125, v125, v197
	v_lshlrev_b32_e32 v195, 16, v174
	v_and_b32_e32 v197, 0xffff0000, v174
	v_add_f32_e32 v126, v126, v195
	v_add_f32_e32 v127, v127, v197
	v_lshlrev_b32_e32 v195, 16, v175
	v_and_b32_e32 v197, 0xffff0000, v175
	v_add_f32_e32 v128, v128, v195
	v_add_f32_e32 v129, v129, v197
	v_lshlrev_b32_e32 v195, 16, v176
	v_and_b32_e32 v197, 0xffff0000, v176
	v_add_f32_e32 v130, v130, v195
	v_add_f32_e32 v131, v131, v197
	v_lshlrev_b32_e32 v195, 16, v177
	v_and_b32_e32 v197, 0xffff0000, v177
	v_add_f32_e32 v132, v132, v195
	v_add_f32_e32 v133, v133, v197
	v_lshlrev_b32_e32 v195, 16, v178
	v_and_b32_e32 v197, 0xffff0000, v178
	v_add_f32_e32 v134, v134, v195
	v_add_f32_e32 v135, v135, v197
	v_lshlrev_b32_e32 v195, 16, v179
	v_and_b32_e32 v197, 0xffff0000, v179
	v_add_f32_e32 v136, v136, v195
	v_add_f32_e32 v137, v137, v197
	v_lshlrev_b32_e32 v195, 16, v180
	v_and_b32_e32 v197, 0xffff0000, v180
	v_add_f32_e32 v138, v138, v195
	v_add_f32_e32 v139, v139, v197
	v_lshlrev_b32_e32 v195, 16, v181
	v_and_b32_e32 v197, 0xffff0000, v181
	v_add_f32_e32 v140, v140, v195
	v_add_f32_e32 v141, v141, v197
	v_lshlrev_b32_e32 v195, 16, v182
	v_and_b32_e32 v197, 0xffff0000, v182
	v_add_f32_e32 v142, v142, v195
	v_add_f32_e32 v143, v143, v197
	v_lshlrev_b32_e32 v195, 16, v183
	v_and_b32_e32 v197, 0xffff0000, v183
	v_add_f32_e32 v144, v144, v195
	v_add_f32_e32 v145, v145, v197
	v_lshlrev_b32_e32 v195, 16, v184
	v_and_b32_e32 v197, 0xffff0000, v184
	v_add_f32_e32 v146, v146, v195
	v_add_f32_e32 v147, v147, v197
	v_lshlrev_b32_e32 v195, 16, v185
	v_and_b32_e32 v197, 0xffff0000, v185
	v_add_f32_e32 v148, v148, v195
	v_add_f32_e32 v149, v149, v197
	global_load_dwordx4 v[170:173], v194, s[12:13]
	global_load_dwordx4 v[174:177], v194, s[12:13] offset:16
	global_load_dwordx4 v[178:181], v194, s[12:13] offset:2048
	global_load_dwordx4 v[182:185], v194, s[12:13] offset:2064
	s_waitcnt vmcnt(12)
	v_lshlrev_b32_e32 v195, 16, v186
	v_and_b32_e32 v197, 0xffff0000, v186
	v_add_f32_e32 v118, v118, v195
	v_add_f32_e32 v119, v119, v197
	v_lshlrev_b32_e32 v195, 16, v187
	v_and_b32_e32 v197, 0xffff0000, v187
	v_add_f32_e32 v120, v120, v195
	v_add_f32_e32 v121, v121, v197
	v_lshlrev_b32_e32 v195, 16, v188
	v_and_b32_e32 v197, 0xffff0000, v188
	v_add_f32_e32 v122, v122, v195
	v_add_f32_e32 v123, v123, v197
	v_lshlrev_b32_e32 v195, 16, v189
	v_and_b32_e32 v197, 0xffff0000, v189
	v_add_f32_e32 v124, v124, v195
	v_add_f32_e32 v125, v125, v197
	v_lshlrev_b32_e32 v195, 16, v190
	v_and_b32_e32 v197, 0xffff0000, v190
	v_add_f32_e32 v126, v126, v195
	v_add_f32_e32 v127, v127, v197
	v_lshlrev_b32_e32 v195, 16, v191
	v_and_b32_e32 v197, 0xffff0000, v191
	v_add_f32_e32 v128, v128, v195
	v_add_f32_e32 v129, v129, v197
	v_lshlrev_b32_e32 v195, 16, v192
	v_and_b32_e32 v197, 0xffff0000, v192
	v_add_f32_e32 v130, v130, v195
	v_add_f32_e32 v131, v131, v197
	v_lshlrev_b32_e32 v195, 16, v193
	v_and_b32_e32 v197, 0xffff0000, v193
	v_add_f32_e32 v132, v132, v195
	v_add_f32_e32 v133, v133, v197
	v_lshlrev_b32_e32 v195, 16, v198
	v_and_b32_e32 v197, 0xffff0000, v198
	v_add_f32_e32 v134, v134, v195
	v_add_f32_e32 v135, v135, v197
	v_lshlrev_b32_e32 v195, 16, v199
	v_and_b32_e32 v197, 0xffff0000, v199
	v_add_f32_e32 v136, v136, v195
	v_add_f32_e32 v137, v137, v197
	v_lshlrev_b32_e32 v195, 16, v200
	v_and_b32_e32 v197, 0xffff0000, v200
	v_add_f32_e32 v138, v138, v195
	v_add_f32_e32 v139, v139, v197
	v_lshlrev_b32_e32 v195, 16, v201
	v_and_b32_e32 v197, 0xffff0000, v201
	v_add_f32_e32 v140, v140, v195
	v_add_f32_e32 v141, v141, v197
	v_lshlrev_b32_e32 v195, 16, v202
	v_and_b32_e32 v197, 0xffff0000, v202
	v_add_f32_e32 v142, v142, v195
	v_add_f32_e32 v143, v143, v197
	v_lshlrev_b32_e32 v195, 16, v203
	v_and_b32_e32 v197, 0xffff0000, v203
	v_add_f32_e32 v144, v144, v195
	v_add_f32_e32 v145, v145, v197
	v_lshlrev_b32_e32 v195, 16, v204
	v_and_b32_e32 v197, 0xffff0000, v204
	v_add_f32_e32 v146, v146, v195
	v_add_f32_e32 v147, v147, v197
	v_lshlrev_b32_e32 v195, 16, v205
	v_and_b32_e32 v197, 0xffff0000, v205
	v_add_f32_e32 v148, v148, v195
	v_add_f32_e32 v149, v149, v197
	s_waitcnt vmcnt(8)
	v_lshlrev_b32_e32 v195, 16, v206
	v_and_b32_e32 v197, 0xffff0000, v206
	v_add_f32_e32 v118, v118, v195
	v_add_f32_e32 v119, v119, v197
	v_lshlrev_b32_e32 v195, 16, v207
	v_and_b32_e32 v197, 0xffff0000, v207
	v_add_f32_e32 v120, v120, v195
	v_add_f32_e32 v121, v121, v197
	v_lshlrev_b32_e32 v195, 16, v208
	v_and_b32_e32 v197, 0xffff0000, v208
	v_add_f32_e32 v122, v122, v195
	v_add_f32_e32 v123, v123, v197
	v_lshlrev_b32_e32 v195, 16, v209
	v_and_b32_e32 v197, 0xffff0000, v209
	v_add_f32_e32 v124, v124, v195
	v_add_f32_e32 v125, v125, v197
	v_lshlrev_b32_e32 v195, 16, v210
	v_and_b32_e32 v197, 0xffff0000, v210
	v_add_f32_e32 v126, v126, v195
	v_add_f32_e32 v127, v127, v197
	v_lshlrev_b32_e32 v195, 16, v211
	v_and_b32_e32 v197, 0xffff0000, v211
	v_add_f32_e32 v128, v128, v195
	v_add_f32_e32 v129, v129, v197
	v_lshlrev_b32_e32 v195, 16, v212
	v_and_b32_e32 v197, 0xffff0000, v212
	v_add_f32_e32 v130, v130, v195
	v_add_f32_e32 v131, v131, v197
	v_lshlrev_b32_e32 v195, 16, v213
	v_and_b32_e32 v197, 0xffff0000, v213
	v_add_f32_e32 v132, v132, v195
	v_add_f32_e32 v133, v133, v197
	v_lshlrev_b32_e32 v195, 16, v214
	v_and_b32_e32 v197, 0xffff0000, v214
	v_add_f32_e32 v134, v134, v195
	v_add_f32_e32 v135, v135, v197
	v_lshlrev_b32_e32 v195, 16, v215
	v_and_b32_e32 v197, 0xffff0000, v215
	v_add_f32_e32 v136, v136, v195
	v_add_f32_e32 v137, v137, v197
	v_lshlrev_b32_e32 v195, 16, v216
	v_and_b32_e32 v197, 0xffff0000, v216
	v_add_f32_e32 v138, v138, v195
	v_add_f32_e32 v139, v139, v197
	v_lshlrev_b32_e32 v195, 16, v217
	v_and_b32_e32 v197, 0xffff0000, v217
	v_add_f32_e32 v140, v140, v195
	v_add_f32_e32 v141, v141, v197
	v_lshlrev_b32_e32 v195, 16, v218
	v_and_b32_e32 v197, 0xffff0000, v218
	v_add_f32_e32 v142, v142, v195
	v_add_f32_e32 v143, v143, v197
	v_lshlrev_b32_e32 v195, 16, v219
	v_and_b32_e32 v197, 0xffff0000, v219
	v_add_f32_e32 v144, v144, v195
	v_add_f32_e32 v145, v145, v197
	v_lshlrev_b32_e32 v195, 16, v220
	v_and_b32_e32 v197, 0xffff0000, v220
	v_add_f32_e32 v146, v146, v195
	v_add_f32_e32 v147, v147, v197
	v_lshlrev_b32_e32 v195, 16, v221
	v_and_b32_e32 v197, 0xffff0000, v221
	v_add_f32_e32 v148, v148, v195
	v_add_f32_e32 v149, v149, v197
	s_lshl_b32 s97, s32, 12
	s_add_u32 s94, s34, s97
	s_addc_u32 s95, s35, 0
	s_add_u32 s94, s94, 0x2aa00000
	s_addc_u32 s95, s95, 0
	v_cvt_pk_bf16_f32 v186, v118, v119
	v_cvt_pk_bf16_f32 v187, v120, v121
	v_cvt_pk_bf16_f32 v188, v122, v123
	v_cvt_pk_bf16_f32 v189, v124, v125
	global_store_dwordx4 v162, v[186:189], s[94:95]
	v_cvt_pk_bf16_f32 v190, v126, v127
	v_cvt_pk_bf16_f32 v191, v128, v129
	v_cvt_pk_bf16_f32 v192, v130, v131
	v_cvt_pk_bf16_f32 v193, v132, v133
	global_store_dwordx4 v162, v[190:193], s[94:95] offset:1024
	v_cvt_pk_bf16_f32 v198, v134, v135
	v_cvt_pk_bf16_f32 v199, v136, v137
	v_cvt_pk_bf16_f32 v200, v138, v139
	v_cvt_pk_bf16_f32 v201, v140, v141
	global_store_dwordx4 v162, v[198:201], s[94:95] offset:2048
	v_cvt_pk_bf16_f32 v202, v142, v143
	v_cvt_pk_bf16_f32 v203, v144, v145
	v_cvt_pk_bf16_f32 v204, v146, v147
	v_cvt_pk_bf16_f32 v205, v148, v149
	global_store_dwordx4 v162, v[202:205], s[94:95] offset:3072
	v_lshlrev_b32_e32 v118, 16, v186
	v_and_b32_e32 v119, 0xffff0000, v186
	v_lshlrev_b32_e32 v120, 16, v187
	v_and_b32_e32 v121, 0xffff0000, v187
	v_lshlrev_b32_e32 v122, 16, v188
	v_and_b32_e32 v123, 0xffff0000, v188
	v_lshlrev_b32_e32 v124, 16, v189
	v_and_b32_e32 v125, 0xffff0000, v189
	v_lshlrev_b32_e32 v126, 16, v190
	v_and_b32_e32 v127, 0xffff0000, v190
	v_lshlrev_b32_e32 v128, 16, v191
	v_and_b32_e32 v129, 0xffff0000, v191
	v_lshlrev_b32_e32 v130, 16, v192
	v_and_b32_e32 v131, 0xffff0000, v192
	v_lshlrev_b32_e32 v132, 16, v193
	v_and_b32_e32 v133, 0xffff0000, v193
	v_lshlrev_b32_e32 v134, 16, v198
	v_and_b32_e32 v135, 0xffff0000, v198
	v_lshlrev_b32_e32 v136, 16, v199
	v_and_b32_e32 v137, 0xffff0000, v199
	v_lshlrev_b32_e32 v138, 16, v200
	v_and_b32_e32 v139, 0xffff0000, v200
	v_lshlrev_b32_e32 v140, 16, v201
	v_and_b32_e32 v141, 0xffff0000, v201
	v_lshlrev_b32_e32 v142, 16, v202
	v_and_b32_e32 v143, 0xffff0000, v202
	v_lshlrev_b32_e32 v144, 16, v203
	v_and_b32_e32 v145, 0xffff0000, v203
	v_lshlrev_b32_e32 v146, 16, v204
	v_and_b32_e32 v147, 0xffff0000, v204
	v_lshlrev_b32_e32 v148, 16, v205
	v_and_b32_e32 v149, 0xffff0000, v205
	v_mul_f32_e32 v227, v118, v118
	v_fmac_f32_e32 v227, v119, v119
	v_fmac_f32_e32 v227, v120, v120
	v_fmac_f32_e32 v227, v121, v121
	v_fmac_f32_e32 v227, v122, v122
	v_fmac_f32_e32 v227, v123, v123
	v_fmac_f32_e32 v227, v124, v124
	v_fmac_f32_e32 v227, v125, v125
	v_fmac_f32_e32 v227, v126, v126
	v_fmac_f32_e32 v227, v127, v127
	v_fmac_f32_e32 v227, v128, v128
	v_fmac_f32_e32 v227, v129, v129
	v_fmac_f32_e32 v227, v130, v130
	v_fmac_f32_e32 v227, v131, v131
	v_fmac_f32_e32 v227, v132, v132
	v_fmac_f32_e32 v227, v133, v133
	v_fmac_f32_e32 v227, v134, v134
	v_fmac_f32_e32 v227, v135, v135
	v_fmac_f32_e32 v227, v136, v136
	v_fmac_f32_e32 v227, v137, v137
	v_fmac_f32_e32 v227, v138, v138
	v_fmac_f32_e32 v227, v139, v139
	v_fmac_f32_e32 v227, v140, v140
	v_fmac_f32_e32 v227, v141, v141
	v_fmac_f32_e32 v227, v142, v142
	v_fmac_f32_e32 v227, v143, v143
	v_fmac_f32_e32 v227, v144, v144
	v_fmac_f32_e32 v227, v145, v145
	v_fmac_f32_e32 v227, v146, v146
	v_fmac_f32_e32 v227, v147, v147
	v_fmac_f32_e32 v227, v148, v148
	v_fmac_f32_e32 v227, v149, v149
	v_xor_b32_e32 v195, 4, v243
	ds_bpermute_b32 v242, v195, v227
	s_waitcnt lgkmcnt(0)
	v_add_f32_e32 v227, v227, v242
	v_xor_b32_e32 v195, 8, v243
	ds_bpermute_b32 v242, v195, v227
	s_waitcnt lgkmcnt(0)
	v_add_f32_e32 v227, v227, v242
	v_xor_b32_e32 v195, 16, v243
	ds_bpermute_b32 v242, v195, v227
	s_waitcnt lgkmcnt(0)
	v_add_f32_e32 v227, v227, v242
	v_xor_b32_e32 v195, 32, v243
	ds_bpermute_b32 v242, v195, v227
	s_waitcnt lgkmcnt(0)
	v_add_f32_e32 v227, v227, v242
	v_xor_b32_e32 v195, 64, v243
	ds_bpermute_b32 v242, v195, v227
	s_waitcnt lgkmcnt(0)
	v_add_f32_e32 v227, v227, v242
	v_xor_b32_e32 v195, 128, v243
	ds_bpermute_b32 v242, v195, v227
	s_waitcnt lgkmcnt(0)
	v_add_f32_e32 v227, v227, v242
	v_mov_b32_e32 v240, 0x3a000000
	v_mov_b32_e32 v241, 0x358637bd
	v_fma_f32 v227, v227, v240, v241
	v_rsq_f32_e32 v227, v227
	s_lshl_b32 s97, s32, 12
	s_add_u32 s100, s34, s97
	s_addc_u32 s101, s35, 0
	s_add_u32 s100, s100, 0x9800000
	s_addc_u32 s101, s101, 0
	s_waitcnt vmcnt(4)
	v_mul_f32_e32 v118, v118, v227
	v_mul_f32_e32 v118, v118, v150
	v_mul_f32_e32 v119, v119, v227
	v_mul_f32_e32 v119, v119, v151
	v_mul_f32_e32 v120, v120, v227
	v_mul_f32_e32 v120, v120, v152
	v_mul_f32_e32 v121, v121, v227
	v_mul_f32_e32 v121, v121, v153
	v_mul_f32_e32 v122, v122, v227
	v_mul_f32_e32 v122, v122, v154
	v_mul_f32_e32 v123, v123, v227
	v_mul_f32_e32 v123, v123, v155
	v_mul_f32_e32 v124, v124, v227
	v_mul_f32_e32 v124, v124, v156
	v_mul_f32_e32 v125, v125, v227
	v_mul_f32_e32 v125, v125, v157
	v_mul_f32_e32 v126, v126, v227
	v_mul_f32_e32 v126, v126, v158
	v_mul_f32_e32 v127, v127, v227
	v_mul_f32_e32 v127, v127, v159
	v_mul_f32_e32 v128, v128, v227
	v_mul_f32_e32 v128, v128, v160
	v_mul_f32_e32 v129, v129, v227
	v_mul_f32_e32 v129, v129, v161
	v_mul_f32_e32 v130, v130, v227
	v_mul_f32_e32 v130, v130, v166
	v_mul_f32_e32 v131, v131, v227
	v_mul_f32_e32 v131, v131, v167
	v_mul_f32_e32 v132, v132, v227
	v_mul_f32_e32 v132, v132, v168
	v_mul_f32_e32 v133, v133, v227
	v_mul_f32_e32 v133, v133, v169
	v_mul_f32_e32 v134, v134, v227
	v_mul_f32_e32 v134, v134, v170
	v_mul_f32_e32 v135, v135, v227
	v_mul_f32_e32 v135, v135, v171
	v_mul_f32_e32 v136, v136, v227
	v_mul_f32_e32 v136, v136, v172
	v_mul_f32_e32 v137, v137, v227
	v_mul_f32_e32 v137, v137, v173
	v_mul_f32_e32 v138, v138, v227
	v_mul_f32_e32 v138, v138, v174
	v_mul_f32_e32 v139, v139, v227
	v_mul_f32_e32 v139, v139, v175
	v_mul_f32_e32 v140, v140, v227
	v_mul_f32_e32 v140, v140, v176
	v_mul_f32_e32 v141, v141, v227
	v_mul_f32_e32 v141, v141, v177
	v_mul_f32_e32 v142, v142, v227
	v_mul_f32_e32 v142, v142, v178
	v_mul_f32_e32 v143, v143, v227
	v_mul_f32_e32 v143, v143, v179
	v_mul_f32_e32 v144, v144, v227
	v_mul_f32_e32 v144, v144, v180
	v_mul_f32_e32 v145, v145, v227
	v_mul_f32_e32 v145, v145, v181
	v_mul_f32_e32 v146, v146, v227
	v_mul_f32_e32 v146, v146, v182
	v_mul_f32_e32 v147, v147, v227
	v_mul_f32_e32 v147, v147, v183
	v_mul_f32_e32 v148, v148, v227
	v_mul_f32_e32 v148, v148, v184
	v_mul_f32_e32 v149, v149, v227
	v_mul_f32_e32 v149, v149, v185
	v_cvt_pk_bf16_f32 v206, v118, v119
	v_cvt_pk_bf16_f32 v207, v120, v121
	v_cvt_pk_bf16_f32 v208, v122, v123
	v_cvt_pk_bf16_f32 v209, v124, v125
	global_store_dwordx4 v162, v[206:209], s[100:101]
	v_cvt_pk_bf16_f32 v210, v126, v127
	v_cvt_pk_bf16_f32 v211, v128, v129
	v_cvt_pk_bf16_f32 v212, v130, v131
	v_cvt_pk_bf16_f32 v213, v132, v133
	global_store_dwordx4 v162, v[210:213], s[100:101] offset:1024
	v_cvt_pk_bf16_f32 v214, v134, v135
	v_cvt_pk_bf16_f32 v215, v136, v137
	v_cvt_pk_bf16_f32 v216, v138, v139
	v_cvt_pk_bf16_f32 v217, v140, v141
	global_store_dwordx4 v162, v[214:217], s[100:101] offset:2048
	v_cvt_pk_bf16_f32 v218, v142, v143
	v_cvt_pk_bf16_f32 v219, v144, v145
	v_cvt_pk_bf16_f32 v220, v146, v147
	v_cvt_pk_bf16_f32 v221, v148, v149
	global_store_dwordx4 v162, v[218:221], s[100:101] offset:3072
	s_branch .LBB0_1042

.LBB0_1293:
	s_cmpk_lg_i32 s26, 0x100
	s_cbranch_scc1 .Lsrow_r3_orig
	s_add_i32 s93, s24, 0xffffe000
	s_and_b32 s97, s93, 7
	s_cmp_gt_u32 s97, 3
	s_cbranch_scc1 .LBB0_1307
	s_lshr_b32 s93, s93, 3
	s_lshl_b32 s93, s93, 2
	s_add_i32 s93, s93, s97
	s_add_i32 s32, s93, 0x2000
	s_waitcnt lgkmcnt(0)
	v_and_b32_e32 v195, 63, v164
	v_lshlrev_b32_e32 v162, 4, v195
	v_lshlrev_b32_e32 v163, 5, v195
	v_lshlrev_b32_e32 v243, 2, v195
	v_add_u32_e32 v194, 0x1000, v163
	s_lshl_b32 s97, s93, 12
	s_add_u32 s98, s34, s97
	s_addc_u32 s99, s35, 0
	s_add_u32 s98, s98, 0x19600000
	s_addc_u32 s99, s99, 0
	s_lshl_b32 s97, s32, 12
	s_add_u32 s94, s34, s97
	s_addc_u32 s95, s35, 0
	s_add_u32 s94, s94, 0x2aa00000
	s_addc_u32 s95, s95, 0
	global_load_dwordx4 v[222:225], v162, s[94:95]
	global_load_dwordx4 v[228:231], v162, s[94:95] offset:1024
	global_load_dwordx4 v[232:235], v162, s[94:95] offset:2048
	global_load_dwordx4 v[236:239], v162, s[94:95] offset:3072
	global_load_dwordx4 v[150:153], v162, s[98:99]
	global_load_dwordx4 v[154:157], v162, s[98:99] offset:1024
	global_load_dwordx4 v[158:161], v162, s[98:99] offset:2048
	global_load_dwordx4 v[166:169], v162, s[98:99] offset:3072
	s_add_u32 s98, s98, 0x400000
	s_addc_u32 s99, s99, 0
	global_load_dwordx4 v[170:173], v162, s[98:99]
	global_load_dwordx4 v[174:177], v162, s[98:99] offset:1024
	global_load_dwordx4 v[178:181], v162, s[98:99] offset:2048
	global_load_dwordx4 v[182:185], v162, s[98:99] offset:3072
	s_add_u32 s98, s98, 0x400000
	s_addc_u32 s99, s99, 0
	global_load_dwordx4 v[186:189], v162, s[98:99]
	global_load_dwordx4 v[190:193], v162, s[98:99] offset:1024
	global_load_dwordx4 v[198:201], v162, s[98:99] offset:2048
	global_load_dwordx4 v[202:205], v162, s[98:99] offset:3072
	s_add_u32 s98, s98, 0x400000
	s_addc_u32 s99, s99, 0
	global_load_dwordx4 v[206:209], v162, s[98:99]
	global_load_dwordx4 v[210:213], v162, s[98:99] offset:1024
	global_load_dwordx4 v[214:217], v162, s[98:99] offset:2048
	global_load_dwordx4 v[218:221], v162, s[98:99] offset:3072
	s_add_u32 s98, s98, 0x400000
	s_addc_u32 s99, s99, 0
	s_waitcnt vmcnt(16)
	v_lshlrev_b32_e32 v118, 16, v222
	v_and_b32_e32 v119, 0xffff0000, v222
	v_lshlrev_b32_e32 v120, 16, v223
	v_and_b32_e32 v121, 0xffff0000, v223
	v_lshlrev_b32_e32 v122, 16, v224
	v_and_b32_e32 v123, 0xffff0000, v224
	v_lshlrev_b32_e32 v124, 16, v225
	v_and_b32_e32 v125, 0xffff0000, v225
	v_lshlrev_b32_e32 v126, 16, v228
	v_and_b32_e32 v127, 0xffff0000, v228
	v_lshlrev_b32_e32 v128, 16, v229
	v_and_b32_e32 v129, 0xffff0000, v229
	v_lshlrev_b32_e32 v130, 16, v230
	v_and_b32_e32 v131, 0xffff0000, v230
	v_lshlrev_b32_e32 v132, 16, v231
	v_and_b32_e32 v133, 0xffff0000, v231
	v_lshlrev_b32_e32 v134, 16, v232
	v_and_b32_e32 v135, 0xffff0000, v232
	v_lshlrev_b32_e32 v136, 16, v233
	v_and_b32_e32 v137, 0xffff0000, v233
	v_lshlrev_b32_e32 v138, 16, v234
	v_and_b32_e32 v139, 0xffff0000, v234
	v_lshlrev_b32_e32 v140, 16, v235
	v_and_b32_e32 v141, 0xffff0000, v235
	v_lshlrev_b32_e32 v142, 16, v236
	v_and_b32_e32 v143, 0xffff0000, v236
	v_lshlrev_b32_e32 v144, 16, v237
	v_and_b32_e32 v145, 0xffff0000, v237
	v_lshlrev_b32_e32 v146, 16, v238
	v_and_b32_e32 v147, 0xffff0000, v238
	v_lshlrev_b32_e32 v148, 16, v239
	v_and_b32_e32 v149, 0xffff0000, v239
	s_waitcnt vmcnt(12)
	v_lshlrev_b32_e32 v195, 16, v150
	v_and_b32_e32 v197, 0xffff0000, v150
	v_add_f32_e32 v118, v118, v195
	v_add_f32_e32 v119, v119, v197
	v_lshlrev_b32_e32 v195, 16, v151
	v_and_b32_e32 v197, 0xffff0000, v151
	v_add_f32_e32 v120, v120, v195
	v_add_f32_e32 v121, v121, v197
	v_lshlrev_b32_e32 v195, 16, v152
	v_and_b32_e32 v197, 0xffff0000, v152
	v_add_f32_e32 v122, v122, v195
	v_add_f32_e32 v123, v123, v197
	v_lshlrev_b32_e32 v195, 16, v153
	v_and_b32_e32 v197, 0xffff0000, v153
	v_add_f32_e32 v124, v124, v195
	v_add_f32_e32 v125, v125, v197
	v_lshlrev_b32_e32 v195, 16, v154
	v_and_b32_e32 v197, 0xffff0000, v154
	v_add_f32_e32 v126, v126, v195
	v_add_f32_e32 v127, v127, v197
	v_lshlrev_b32_e32 v195, 16, v155
	v_and_b32_e32 v197, 0xffff0000, v155
	v_add_f32_e32 v128, v128, v195
	v_add_f32_e32 v129, v129, v197
	v_lshlrev_b32_e32 v195, 16, v156
	v_and_b32_e32 v197, 0xffff0000, v156
	v_add_f32_e32 v130, v130, v195
	v_add_f32_e32 v131, v131, v197
	v_lshlrev_b32_e32 v195, 16, v157
	v_and_b32_e32 v197, 0xffff0000, v157
	v_add_f32_e32 v132, v132, v195
	v_add_f32_e32 v133, v133, v197
	v_lshlrev_b32_e32 v195, 16, v158
	v_and_b32_e32 v197, 0xffff0000, v158
	v_add_f32_e32 v134, v134, v195
	v_add_f32_e32 v135, v135, v197
	v_lshlrev_b32_e32 v195, 16, v159
	v_and_b32_e32 v197, 0xffff0000, v159
	v_add_f32_e32 v136, v136, v195
	v_add_f32_e32 v137, v137, v197
	v_lshlrev_b32_e32 v195, 16, v160
	v_and_b32_e32 v197, 0xffff0000, v160
	v_add_f32_e32 v138, v138, v195
	v_add_f32_e32 v139, v139, v197
	v_lshlrev_b32_e32 v195, 16, v161
	v_and_b32_e32 v197, 0xffff0000, v161
	v_add_f32_e32 v140, v140, v195
	v_add_f32_e32 v141, v141, v197
	v_lshlrev_b32_e32 v195, 16, v166
	v_and_b32_e32 v197, 0xffff0000, v166
	v_add_f32_e32 v142, v142, v195
	v_add_f32_e32 v143, v143, v197
	v_lshlrev_b32_e32 v195, 16, v167
	v_and_b32_e32 v197, 0xffff0000, v167
	v_add_f32_e32 v144, v144, v195
	v_add_f32_e32 v145, v145, v197
	v_lshlrev_b32_e32 v195, 16, v168
	v_and_b32_e32 v197, 0xffff0000, v168
	v_add_f32_e32 v146, v146, v195
	v_add_f32_e32 v147, v147, v197
	v_lshlrev_b32_e32 v195, 16, v169
	v_and_b32_e32 v197, 0xffff0000, v169
	v_add_f32_e32 v148, v148, v195
	v_add_f32_e32 v149, v149, v197
	global_load_dwordx4 v[150:153], v162, s[98:99]
	global_load_dwordx4 v[154:157], v162, s[98:99] offset:1024
	global_load_dwordx4 v[158:161], v162, s[98:99] offset:2048
	global_load_dwordx4 v[166:169], v162, s[98:99] offset:3072
	s_add_u32 s98, s98, 0x400000
	s_addc_u32 s99, s99, 0
	s_waitcnt vmcnt(12)
	v_lshlrev_b32_e32 v195, 16, v170
	v_and_b32_e32 v197, 0xffff0000, v170
	v_add_f32_e32 v118, v118, v195
	v_add_f32_e32 v119, v119, v197
	v_lshlrev_b32_e32 v195, 16, v171
	v_and_b32_e32 v197, 0xffff0000, v171
	v_add_f32_e32 v120, v120, v195
	v_add_f32_e32 v121, v121, v197
	v_lshlrev_b32_e32 v195, 16, v172
	v_and_b32_e32 v197, 0xffff0000, v172
	v_add_f32_e32 v122, v122, v195
	v_add_f32_e32 v123, v123, v197
	v_lshlrev_b32_e32 v195, 16, v173
	v_and_b32_e32 v197, 0xffff0000, v173
	v_add_f32_e32 v124, v124, v195
	v_add_f32_e32 v125, v125, v197
	v_lshlrev_b32_e32 v195, 16, v174
	v_and_b32_e32 v197, 0xffff0000, v174
	v_add_f32_e32 v126, v126, v195
	v_add_f32_e32 v127, v127, v197
	v_lshlrev_b32_e32 v195, 16, v175
	v_and_b32_e32 v197, 0xffff0000, v175
	v_add_f32_e32 v128, v128, v195
	v_add_f32_e32 v129, v129, v197
	v_lshlrev_b32_e32 v195, 16, v176
	v_and_b32_e32 v197, 0xffff0000, v176
	v_add_f32_e32 v130, v130, v195
	v_add_f32_e32 v131, v131, v197
	v_lshlrev_b32_e32 v195, 16, v177
	v_and_b32_e32 v197, 0xffff0000, v177
	v_add_f32_e32 v132, v132, v195
	v_add_f32_e32 v133, v133, v197
	v_lshlrev_b32_e32 v195, 16, v178
	v_and_b32_e32 v197, 0xffff0000, v178
	v_add_f32_e32 v134, v134, v195
	v_add_f32_e32 v135, v135, v197
	v_lshlrev_b32_e32 v195, 16, v179
	v_and_b32_e32 v197, 0xffff0000, v179
	v_add_f32_e32 v136, v136, v195
	v_add_f32_e32 v137, v137, v197
	v_lshlrev_b32_e32 v195, 16, v180
	v_and_b32_e32 v197, 0xffff0000, v180
	v_add_f32_e32 v138, v138, v195
	v_add_f32_e32 v139, v139, v197
	v_lshlrev_b32_e32 v195, 16, v181
	v_and_b32_e32 v197, 0xffff0000, v181
	v_add_f32_e32 v140, v140, v195
	v_add_f32_e32 v141, v141, v197
	v_lshlrev_b32_e32 v195, 16, v182
	v_and_b32_e32 v197, 0xffff0000, v182
	v_add_f32_e32 v142, v142, v195
	v_add_f32_e32 v143, v143, v197
	v_lshlrev_b32_e32 v195, 16, v183
	v_and_b32_e32 v197, 0xffff0000, v183
	v_add_f32_e32 v144, v144, v195
	v_add_f32_e32 v145, v145, v197
	v_lshlrev_b32_e32 v195, 16, v184
	v_and_b32_e32 v197, 0xffff0000, v184
	v_add_f32_e32 v146, v146, v195
	v_add_f32_e32 v147, v147, v197
	v_lshlrev_b32_e32 v195, 16, v185
	v_and_b32_e32 v197, 0xffff0000, v185
	v_add_f32_e32 v148, v148, v195
	v_add_f32_e32 v149, v149, v197
	global_load_dwordx4 v[170:173], v162, s[98:99]
	global_load_dwordx4 v[174:177], v162, s[98:99] offset:1024
	global_load_dwordx4 v[178:181], v162, s[98:99] offset:2048
	global_load_dwordx4 v[182:185], v162, s[98:99] offset:3072
	s_add_u32 s98, s98, 0x400000
	s_addc_u32 s99, s99, 0
	s_waitcnt vmcnt(12)
	v_lshlrev_b32_e32 v195, 16, v186
	v_and_b32_e32 v197, 0xffff0000, v186
	v_add_f32_e32 v118, v118, v195
	v_add_f32_e32 v119, v119, v197
	v_lshlrev_b32_e32 v195, 16, v187
	v_and_b32_e32 v197, 0xffff0000, v187
	v_add_f32_e32 v120, v120, v195
	v_add_f32_e32 v121, v121, v197
	v_lshlrev_b32_e32 v195, 16, v188
	v_and_b32_e32 v197, 0xffff0000, v188
	v_add_f32_e32 v122, v122, v195
	v_add_f32_e32 v123, v123, v197
	v_lshlrev_b32_e32 v195, 16, v189
	v_and_b32_e32 v197, 0xffff0000, v189
	v_add_f32_e32 v124, v124, v195
	v_add_f32_e32 v125, v125, v197
	v_lshlrev_b32_e32 v195, 16, v190
	v_and_b32_e32 v197, 0xffff0000, v190
	v_add_f32_e32 v126, v126, v195
	v_add_f32_e32 v127, v127, v197
	v_lshlrev_b32_e32 v195, 16, v191
	v_and_b32_e32 v197, 0xffff0000, v191
	v_add_f32_e32 v128, v128, v195
	v_add_f32_e32 v129, v129, v197
	v_lshlrev_b32_e32 v195, 16, v192
	v_and_b32_e32 v197, 0xffff0000, v192
	v_add_f32_e32 v130, v130, v195
	v_add_f32_e32 v131, v131, v197
	v_lshlrev_b32_e32 v195, 16, v193
	v_and_b32_e32 v197, 0xffff0000, v193
	v_add_f32_e32 v132, v132, v195
	v_add_f32_e32 v133, v133, v197
	v_lshlrev_b32_e32 v195, 16, v198
	v_and_b32_e32 v197, 0xffff0000, v198
	v_add_f32_e32 v134, v134, v195
	v_add_f32_e32 v135, v135, v197
	v_lshlrev_b32_e32 v195, 16, v199
	v_and_b32_e32 v197, 0xffff0000, v199
	v_add_f32_e32 v136, v136, v195
	v_add_f32_e32 v137, v137, v197
	v_lshlrev_b32_e32 v195, 16, v200
	v_and_b32_e32 v197, 0xffff0000, v200
	v_add_f32_e32 v138, v138, v195
	v_add_f32_e32 v139, v139, v197
	v_lshlrev_b32_e32 v195, 16, v201
	v_and_b32_e32 v197, 0xffff0000, v201
	v_add_f32_e32 v140, v140, v195
	v_add_f32_e32 v141, v141, v197
	v_lshlrev_b32_e32 v195, 16, v202
	v_and_b32_e32 v197, 0xffff0000, v202
	v_add_f32_e32 v142, v142, v195
	v_add_f32_e32 v143, v143, v197
	v_lshlrev_b32_e32 v195, 16, v203
	v_and_b32_e32 v197, 0xffff0000, v203
	v_add_f32_e32 v144, v144, v195
	v_add_f32_e32 v145, v145, v197
	v_lshlrev_b32_e32 v195, 16, v204
	v_and_b32_e32 v197, 0xffff0000, v204
	v_add_f32_e32 v146, v146, v195
	v_add_f32_e32 v147, v147, v197
	v_lshlrev_b32_e32 v195, 16, v205
	v_and_b32_e32 v197, 0xffff0000, v205
	v_add_f32_e32 v148, v148, v195
	v_add_f32_e32 v149, v149, v197
	global_load_dwordx4 v[186:189], v162, s[98:99]
	global_load_dwordx4 v[190:193], v162, s[98:99] offset:1024
	global_load_dwordx4 v[198:201], v162, s[98:99] offset:2048
	global_load_dwordx4 v[202:205], v162, s[98:99] offset:3072
	s_add_u32 s98, s98, 0x400000
	s_addc_u32 s99, s99, 0
	s_waitcnt vmcnt(12)
	v_lshlrev_b32_e32 v195, 16, v206
	v_and_b32_e32 v197, 0xffff0000, v206
	v_add_f32_e32 v118, v118, v195
	v_add_f32_e32 v119, v119, v197
	v_lshlrev_b32_e32 v195, 16, v207
	v_and_b32_e32 v197, 0xffff0000, v207
	v_add_f32_e32 v120, v120, v195
	v_add_f32_e32 v121, v121, v197
	v_lshlrev_b32_e32 v195, 16, v208
	v_and_b32_e32 v197, 0xffff0000, v208
	v_add_f32_e32 v122, v122, v195
	v_add_f32_e32 v123, v123, v197
	v_lshlrev_b32_e32 v195, 16, v209
	v_and_b32_e32 v197, 0xffff0000, v209
	v_add_f32_e32 v124, v124, v195
	v_add_f32_e32 v125, v125, v197
	v_lshlrev_b32_e32 v195, 16, v210
	v_and_b32_e32 v197, 0xffff0000, v210
	v_add_f32_e32 v126, v126, v195
	v_add_f32_e32 v127, v127, v197
	v_lshlrev_b32_e32 v195, 16, v211
	v_and_b32_e32 v197, 0xffff0000, v211
	v_add_f32_e32 v128, v128, v195
	v_add_f32_e32 v129, v129, v197
	v_lshlrev_b32_e32 v195, 16, v212
	v_and_b32_e32 v197, 0xffff0000, v212
	v_add_f32_e32 v130, v130, v195
	v_add_f32_e32 v131, v131, v197
	v_lshlrev_b32_e32 v195, 16, v213
	v_and_b32_e32 v197, 0xffff0000, v213
	v_add_f32_e32 v132, v132, v195
	v_add_f32_e32 v133, v133, v197
	v_lshlrev_b32_e32 v195, 16, v214
	v_and_b32_e32 v197, 0xffff0000, v214
	v_add_f32_e32 v134, v134, v195
	v_add_f32_e32 v135, v135, v197
	v_lshlrev_b32_e32 v195, 16, v215
	v_and_b32_e32 v197, 0xffff0000, v215
	v_add_f32_e32 v136, v136, v195
	v_add_f32_e32 v137, v137, v197
	v_lshlrev_b32_e32 v195, 16, v216
	v_and_b32_e32 v197, 0xffff0000, v216
	v_add_f32_e32 v138, v138, v195
	v_add_f32_e32 v139, v139, v197
	v_lshlrev_b32_e32 v195, 16, v217
	v_and_b32_e32 v197, 0xffff0000, v217
	v_add_f32_e32 v140, v140, v195
	v_add_f32_e32 v141, v141, v197
	v_lshlrev_b32_e32 v195, 16, v218
	v_and_b32_e32 v197, 0xffff0000, v218
	v_add_f32_e32 v142, v142, v195
	v_add_f32_e32 v143, v143, v197
	v_lshlrev_b32_e32 v195, 16, v219
	v_and_b32_e32 v197, 0xffff0000, v219
	v_add_f32_e32 v144, v144, v195
	v_add_f32_e32 v145, v145, v197
	v_lshlrev_b32_e32 v195, 16, v220
	v_and_b32_e32 v197, 0xffff0000, v220
	v_add_f32_e32 v146, v146, v195
	v_add_f32_e32 v147, v147, v197
	v_lshlrev_b32_e32 v195, 16, v221
	v_and_b32_e32 v197, 0xffff0000, v221
	v_add_f32_e32 v148, v148, v195
	v_add_f32_e32 v149, v149, v197
	global_load_dwordx4 v[206:209], v162, s[98:99]
	global_load_dwordx4 v[210:213], v162, s[98:99] offset:1024
	global_load_dwordx4 v[214:217], v162, s[98:99] offset:2048
	global_load_dwordx4 v[218:221], v162, s[98:99] offset:3072
	s_add_u32 s98, s98, 0x400000
	s_addc_u32 s99, s99, 0
	s_waitcnt vmcnt(12)
	v_lshlrev_b32_e32 v195, 16, v150
	v_and_b32_e32 v197, 0xffff0000, v150
	v_add_f32_e32 v118, v118, v195
	v_add_f32_e32 v119, v119, v197
	v_lshlrev_b32_e32 v195, 16, v151
	v_and_b32_e32 v197, 0xffff0000, v151
	v_add_f32_e32 v120, v120, v195
	v_add_f32_e32 v121, v121, v197
	v_lshlrev_b32_e32 v195, 16, v152
	v_and_b32_e32 v197, 0xffff0000, v152
	v_add_f32_e32 v122, v122, v195
	v_add_f32_e32 v123, v123, v197
	v_lshlrev_b32_e32 v195, 16, v153
	v_and_b32_e32 v197, 0xffff0000, v153
	v_add_f32_e32 v124, v124, v195
	v_add_f32_e32 v125, v125, v197
	v_lshlrev_b32_e32 v195, 16, v154
	v_and_b32_e32 v197, 0xffff0000, v154
	v_add_f32_e32 v126, v126, v195
	v_add_f32_e32 v127, v127, v197
	v_lshlrev_b32_e32 v195, 16, v155
	v_and_b32_e32 v197, 0xffff0000, v155
	v_add_f32_e32 v128, v128, v195
	v_add_f32_e32 v129, v129, v197
	v_lshlrev_b32_e32 v195, 16, v156
	v_and_b32_e32 v197, 0xffff0000, v156
	v_add_f32_e32 v130, v130, v195
	v_add_f32_e32 v131, v131, v197
	v_lshlrev_b32_e32 v195, 16, v157
	v_and_b32_e32 v197, 0xffff0000, v157
	v_add_f32_e32 v132, v132, v195
	v_add_f32_e32 v133, v133, v197
	v_lshlrev_b32_e32 v195, 16, v158
	v_and_b32_e32 v197, 0xffff0000, v158
	v_add_f32_e32 v134, v134, v195
	v_add_f32_e32 v135, v135, v197
	v_lshlrev_b32_e32 v195, 16, v159
	v_and_b32_e32 v197, 0xffff0000, v159
	v_add_f32_e32 v136, v136, v195
	v_add_f32_e32 v137, v137, v197
	v_lshlrev_b32_e32 v195, 16, v160
	v_and_b32_e32 v197, 0xffff0000, v160
	v_add_f32_e32 v138, v138, v195
	v_add_f32_e32 v139, v139, v197
	v_lshlrev_b32_e32 v195, 16, v161
	v_and_b32_e32 v197, 0xffff0000, v161
	v_add_f32_e32 v140, v140, v195
	v_add_f32_e32 v141, v141, v197
	v_lshlrev_b32_e32 v195, 16, v166
	v_and_b32_e32 v197, 0xffff0000, v166
	v_add_f32_e32 v142, v142, v195
	v_add_f32_e32 v143, v143, v197
	v_lshlrev_b32_e32 v195, 16, v167
	v_and_b32_e32 v197, 0xffff0000, v167
	v_add_f32_e32 v144, v144, v195
	v_add_f32_e32 v145, v145, v197
	v_lshlrev_b32_e32 v195, 16, v168
	v_and_b32_e32 v197, 0xffff0000, v168
	v_add_f32_e32 v146, v146, v195
	v_add_f32_e32 v147, v147, v197
	v_lshlrev_b32_e32 v195, 16, v169
	v_and_b32_e32 v197, 0xffff0000, v169
	v_add_f32_e32 v148, v148, v195
	v_add_f32_e32 v149, v149, v197
	global_load_dwordx4 v[150:153], v163, s[0:1]
	global_load_dwordx4 v[154:157], v163, s[0:1] offset:16
	global_load_dwordx4 v[158:161], v163, s[0:1] offset:2048
	global_load_dwordx4 v[166:169], v163, s[0:1] offset:2064
	s_waitcnt vmcnt(12)
	v_lshlrev_b32_e32 v195, 16, v170
	v_and_b32_e32 v197, 0xffff0000, v170
	v_add_f32_e32 v118, v118, v195
	v_add_f32_e32 v119, v119, v197
	v_lshlrev_b32_e32 v195, 16, v171
	v_and_b32_e32 v197, 0xffff0000, v171
	v_add_f32_e32 v120, v120, v195
	v_add_f32_e32 v121, v121, v197
	v_lshlrev_b32_e32 v195, 16, v172
	v_and_b32_e32 v197, 0xffff0000, v172
	v_add_f32_e32 v122, v122, v195
	v_add_f32_e32 v123, v123, v197
	v_lshlrev_b32_e32 v195, 16, v173
	v_and_b32_e32 v197, 0xffff0000, v173
	v_add_f32_e32 v124, v124, v195
	v_add_f32_e32 v125, v125, v197
	v_lshlrev_b32_e32 v195, 16, v174
	v_and_b32_e32 v197, 0xffff0000, v174
	v_add_f32_e32 v126, v126, v195
	v_add_f32_e32 v127, v127, v197
	v_lshlrev_b32_e32 v195, 16, v175
	v_and_b32_e32 v197, 0xffff0000, v175
	v_add_f32_e32 v128, v128, v195
	v_add_f32_e32 v129, v129, v197
	v_lshlrev_b32_e32 v195, 16, v176
	v_and_b32_e32 v197, 0xffff0000, v176
	v_add_f32_e32 v130, v130, v195
	v_add_f32_e32 v131, v131, v197
	v_lshlrev_b32_e32 v195, 16, v177
	v_and_b32_e32 v197, 0xffff0000, v177
	v_add_f32_e32 v132, v132, v195
	v_add_f32_e32 v133, v133, v197
	v_lshlrev_b32_e32 v195, 16, v178
	v_and_b32_e32 v197, 0xffff0000, v178
	v_add_f32_e32 v134, v134, v195
	v_add_f32_e32 v135, v135, v197
	v_lshlrev_b32_e32 v195, 16, v179
	v_and_b32_e32 v197, 0xffff0000, v179
	v_add_f32_e32 v136, v136, v195
	v_add_f32_e32 v137, v137, v197
	v_lshlrev_b32_e32 v195, 16, v180
	v_and_b32_e32 v197, 0xffff0000, v180
	v_add_f32_e32 v138, v138, v195
	v_add_f32_e32 v139, v139, v197
	v_lshlrev_b32_e32 v195, 16, v181
	v_and_b32_e32 v197, 0xffff0000, v181
	v_add_f32_e32 v140, v140, v195
	v_add_f32_e32 v141, v141, v197
	v_lshlrev_b32_e32 v195, 16, v182
	v_and_b32_e32 v197, 0xffff0000, v182
	v_add_f32_e32 v142, v142, v195
	v_add_f32_e32 v143, v143, v197
	v_lshlrev_b32_e32 v195, 16, v183
	v_and_b32_e32 v197, 0xffff0000, v183
	v_add_f32_e32 v144, v144, v195
	v_add_f32_e32 v145, v145, v197
	v_lshlrev_b32_e32 v195, 16, v184
	v_and_b32_e32 v197, 0xffff0000, v184
	v_add_f32_e32 v146, v146, v195
	v_add_f32_e32 v147, v147, v197
	v_lshlrev_b32_e32 v195, 16, v185
	v_and_b32_e32 v197, 0xffff0000, v185
	v_add_f32_e32 v148, v148, v195
	v_add_f32_e32 v149, v149, v197
	global_load_dwordx4 v[170:173], v194, s[0:1]
	global_load_dwordx4 v[174:177], v194, s[0:1] offset:16
	global_load_dwordx4 v[178:181], v194, s[0:1] offset:2048
	global_load_dwordx4 v[182:185], v194, s[0:1] offset:2064
	s_waitcnt vmcnt(12)
	v_lshlrev_b32_e32 v195, 16, v186
	v_and_b32_e32 v197, 0xffff0000, v186
	v_add_f32_e32 v118, v118, v195
	v_add_f32_e32 v119, v119, v197
	v_lshlrev_b32_e32 v195, 16, v187
	v_and_b32_e32 v197, 0xffff0000, v187
	v_add_f32_e32 v120, v120, v195
	v_add_f32_e32 v121, v121, v197
	v_lshlrev_b32_e32 v195, 16, v188
	v_and_b32_e32 v197, 0xffff0000, v188
	v_add_f32_e32 v122, v122, v195
	v_add_f32_e32 v123, v123, v197
	v_lshlrev_b32_e32 v195, 16, v189
	v_and_b32_e32 v197, 0xffff0000, v189
	v_add_f32_e32 v124, v124, v195
	v_add_f32_e32 v125, v125, v197
	v_lshlrev_b32_e32 v195, 16, v190
	v_and_b32_e32 v197, 0xffff0000, v190
	v_add_f32_e32 v126, v126, v195
	v_add_f32_e32 v127, v127, v197
	v_lshlrev_b32_e32 v195, 16, v191
	v_and_b32_e32 v197, 0xffff0000, v191
	v_add_f32_e32 v128, v128, v195
	v_add_f32_e32 v129, v129, v197
	v_lshlrev_b32_e32 v195, 16, v192
	v_and_b32_e32 v197, 0xffff0000, v192
	v_add_f32_e32 v130, v130, v195
	v_add_f32_e32 v131, v131, v197
	v_lshlrev_b32_e32 v195, 16, v193
	v_and_b32_e32 v197, 0xffff0000, v193
	v_add_f32_e32 v132, v132, v195
	v_add_f32_e32 v133, v133, v197
	v_lshlrev_b32_e32 v195, 16, v198
	v_and_b32_e32 v197, 0xffff0000, v198
	v_add_f32_e32 v134, v134, v195
	v_add_f32_e32 v135, v135, v197
	v_lshlrev_b32_e32 v195, 16, v199
	v_and_b32_e32 v197, 0xffff0000, v199
	v_add_f32_e32 v136, v136, v195
	v_add_f32_e32 v137, v137, v197
	v_lshlrev_b32_e32 v195, 16, v200
	v_and_b32_e32 v197, 0xffff0000, v200
	v_add_f32_e32 v138, v138, v195
	v_add_f32_e32 v139, v139, v197
	v_lshlrev_b32_e32 v195, 16, v201
	v_and_b32_e32 v197, 0xffff0000, v201
	v_add_f32_e32 v140, v140, v195
	v_add_f32_e32 v141, v141, v197
	v_lshlrev_b32_e32 v195, 16, v202
	v_and_b32_e32 v197, 0xffff0000, v202
	v_add_f32_e32 v142, v142, v195
	v_add_f32_e32 v143, v143, v197
	v_lshlrev_b32_e32 v195, 16, v203
	v_and_b32_e32 v197, 0xffff0000, v203
	v_add_f32_e32 v144, v144, v195
	v_add_f32_e32 v145, v145, v197
	v_lshlrev_b32_e32 v195, 16, v204
	v_and_b32_e32 v197, 0xffff0000, v204
	v_add_f32_e32 v146, v146, v195
	v_add_f32_e32 v147, v147, v197
	v_lshlrev_b32_e32 v195, 16, v205
	v_and_b32_e32 v197, 0xffff0000, v205
	v_add_f32_e32 v148, v148, v195
	v_add_f32_e32 v149, v149, v197
	s_waitcnt vmcnt(8)
	v_lshlrev_b32_e32 v195, 16, v206
	v_and_b32_e32 v197, 0xffff0000, v206
	v_add_f32_e32 v118, v118, v195
	v_add_f32_e32 v119, v119, v197
	v_lshlrev_b32_e32 v195, 16, v207
	v_and_b32_e32 v197, 0xffff0000, v207
	v_add_f32_e32 v120, v120, v195
	v_add_f32_e32 v121, v121, v197
	v_lshlrev_b32_e32 v195, 16, v208
	v_and_b32_e32 v197, 0xffff0000, v208
	v_add_f32_e32 v122, v122, v195
	v_add_f32_e32 v123, v123, v197
	v_lshlrev_b32_e32 v195, 16, v209
	v_and_b32_e32 v197, 0xffff0000, v209
	v_add_f32_e32 v124, v124, v195
	v_add_f32_e32 v125, v125, v197
	v_lshlrev_b32_e32 v195, 16, v210
	v_and_b32_e32 v197, 0xffff0000, v210
	v_add_f32_e32 v126, v126, v195
	v_add_f32_e32 v127, v127, v197
	v_lshlrev_b32_e32 v195, 16, v211
	v_and_b32_e32 v197, 0xffff0000, v211
	v_add_f32_e32 v128, v128, v195
	v_add_f32_e32 v129, v129, v197
	v_lshlrev_b32_e32 v195, 16, v212
	v_and_b32_e32 v197, 0xffff0000, v212
	v_add_f32_e32 v130, v130, v195
	v_add_f32_e32 v131, v131, v197
	v_lshlrev_b32_e32 v195, 16, v213
	v_and_b32_e32 v197, 0xffff0000, v213
	v_add_f32_e32 v132, v132, v195
	v_add_f32_e32 v133, v133, v197
	v_lshlrev_b32_e32 v195, 16, v214
	v_and_b32_e32 v197, 0xffff0000, v214
	v_add_f32_e32 v134, v134, v195
	v_add_f32_e32 v135, v135, v197
	v_lshlrev_b32_e32 v195, 16, v215
	v_and_b32_e32 v197, 0xffff0000, v215
	v_add_f32_e32 v136, v136, v195
	v_add_f32_e32 v137, v137, v197
	v_lshlrev_b32_e32 v195, 16, v216
	v_and_b32_e32 v197, 0xffff0000, v216
	v_add_f32_e32 v138, v138, v195
	v_add_f32_e32 v139, v139, v197
	v_lshlrev_b32_e32 v195, 16, v217
	v_and_b32_e32 v197, 0xffff0000, v217
	v_add_f32_e32 v140, v140, v195
	v_add_f32_e32 v141, v141, v197
	v_lshlrev_b32_e32 v195, 16, v218
	v_and_b32_e32 v197, 0xffff0000, v218
	v_add_f32_e32 v142, v142, v195
	v_add_f32_e32 v143, v143, v197
	v_lshlrev_b32_e32 v195, 16, v219
	v_and_b32_e32 v197, 0xffff0000, v219
	v_add_f32_e32 v144, v144, v195
	v_add_f32_e32 v145, v145, v197
	v_lshlrev_b32_e32 v195, 16, v220
	v_and_b32_e32 v197, 0xffff0000, v220
	v_add_f32_e32 v146, v146, v195
	v_add_f32_e32 v147, v147, v197
	v_lshlrev_b32_e32 v195, 16, v221
	v_and_b32_e32 v197, 0xffff0000, v221
	v_add_f32_e32 v148, v148, v195
	v_add_f32_e32 v149, v149, v197
	v_mul_f32_e32 v227, v118, v118
	v_fmac_f32_e32 v227, v119, v119
	v_fmac_f32_e32 v227, v120, v120
	v_fmac_f32_e32 v227, v121, v121
	v_fmac_f32_e32 v227, v122, v122
	v_fmac_f32_e32 v227, v123, v123
	v_fmac_f32_e32 v227, v124, v124
	v_fmac_f32_e32 v227, v125, v125
	v_fmac_f32_e32 v227, v126, v126
	v_fmac_f32_e32 v227, v127, v127
	v_fmac_f32_e32 v227, v128, v128
	v_fmac_f32_e32 v227, v129, v129
	v_fmac_f32_e32 v227, v130, v130
	v_fmac_f32_e32 v227, v131, v131
	v_fmac_f32_e32 v227, v132, v132
	v_fmac_f32_e32 v227, v133, v133
	v_fmac_f32_e32 v227, v134, v134
	v_fmac_f32_e32 v227, v135, v135
	v_fmac_f32_e32 v227, v136, v136
	v_fmac_f32_e32 v227, v137, v137
	v_fmac_f32_e32 v227, v138, v138
	v_fmac_f32_e32 v227, v139, v139
	v_fmac_f32_e32 v227, v140, v140
	v_fmac_f32_e32 v227, v141, v141
	v_fmac_f32_e32 v227, v142, v142
	v_fmac_f32_e32 v227, v143, v143
	v_fmac_f32_e32 v227, v144, v144
	v_fmac_f32_e32 v227, v145, v145
	v_fmac_f32_e32 v227, v146, v146
	v_fmac_f32_e32 v227, v147, v147
	v_fmac_f32_e32 v227, v148, v148
	v_fmac_f32_e32 v227, v149, v149
	v_xor_b32_e32 v195, 4, v243
	ds_bpermute_b32 v242, v195, v227
	s_waitcnt lgkmcnt(0)
	v_add_f32_e32 v227, v227, v242
	v_xor_b32_e32 v195, 8, v243
	ds_bpermute_b32 v242, v195, v227
	s_waitcnt lgkmcnt(0)
	v_add_f32_e32 v227, v227, v242
	v_xor_b32_e32 v195, 16, v243
	ds_bpermute_b32 v242, v195, v227
	s_waitcnt lgkmcnt(0)
	v_add_f32_e32 v227, v227, v242
	v_xor_b32_e32 v195, 32, v243
	ds_bpermute_b32 v242, v195, v227
	s_waitcnt lgkmcnt(0)
	v_add_f32_e32 v227, v227, v242
	v_xor_b32_e32 v195, 64, v243
	ds_bpermute_b32 v242, v195, v227
	s_waitcnt lgkmcnt(0)
	v_add_f32_e32 v227, v227, v242
	v_xor_b32_e32 v195, 128, v243
	ds_bpermute_b32 v242, v195, v227
	s_waitcnt lgkmcnt(0)
	v_add_f32_e32 v227, v227, v242
	v_mov_b32_e32 v240, 0x3a000000
	v_mov_b32_e32 v241, 0x358637bd
	v_fma_f32 v227, v227, v240, v241
	v_rsq_f32_e32 v227, v227
	s_lshl_b32 s97, s32, 13
	s_add_u32 s100, s20, s97
	s_addc_u32 s101, s21, 0
	s_waitcnt vmcnt(0)
	v_mul_f32_e32 v118, v118, v227
	v_mul_f32_e32 v118, v118, v150
	v_mul_f32_e32 v119, v119, v227
	v_mul_f32_e32 v119, v119, v151
	v_mul_f32_e32 v120, v120, v227
	v_mul_f32_e32 v120, v120, v152
	v_mul_f32_e32 v121, v121, v227
	v_mul_f32_e32 v121, v121, v153
	v_mul_f32_e32 v122, v122, v227
	v_mul_f32_e32 v122, v122, v154
	v_mul_f32_e32 v123, v123, v227
	v_mul_f32_e32 v123, v123, v155
	v_mul_f32_e32 v124, v124, v227
	v_mul_f32_e32 v124, v124, v156
	v_mul_f32_e32 v125, v125, v227
	v_mul_f32_e32 v125, v125, v157
	v_mul_f32_e32 v126, v126, v227
	v_mul_f32_e32 v126, v126, v158
	v_mul_f32_e32 v127, v127, v227
	v_mul_f32_e32 v127, v127, v159
	v_mul_f32_e32 v128, v128, v227
	v_mul_f32_e32 v128, v128, v160
	v_mul_f32_e32 v129, v129, v227
	v_mul_f32_e32 v129, v129, v161
	v_mul_f32_e32 v130, v130, v227
	v_mul_f32_e32 v130, v130, v166
	v_mul_f32_e32 v131, v131, v227
	v_mul_f32_e32 v131, v131, v167
	v_mul_f32_e32 v132, v132, v227
	v_mul_f32_e32 v132, v132, v168
	v_mul_f32_e32 v133, v133, v227
	v_mul_f32_e32 v133, v133, v169
	v_mul_f32_e32 v134, v134, v227
	v_mul_f32_e32 v134, v134, v170
	v_mul_f32_e32 v135, v135, v227
	v_mul_f32_e32 v135, v135, v171
	v_mul_f32_e32 v136, v136, v227
	v_mul_f32_e32 v136, v136, v172
	v_mul_f32_e32 v137, v137, v227
	v_mul_f32_e32 v137, v137, v173
	v_mul_f32_e32 v138, v138, v227
	v_mul_f32_e32 v138, v138, v174
	v_mul_f32_e32 v139, v139, v227
	v_mul_f32_e32 v139, v139, v175
	v_mul_f32_e32 v140, v140, v227
	v_mul_f32_e32 v140, v140, v176
	v_mul_f32_e32 v141, v141, v227
	v_mul_f32_e32 v141, v141, v177
	v_mul_f32_e32 v142, v142, v227
	v_mul_f32_e32 v142, v142, v178
	v_mul_f32_e32 v143, v143, v227
	v_mul_f32_e32 v143, v143, v179
	v_mul_f32_e32 v144, v144, v227
	v_mul_f32_e32 v144, v144, v180
	v_mul_f32_e32 v145, v145, v227
	v_mul_f32_e32 v145, v145, v181
	v_mul_f32_e32 v146, v146, v227
	v_mul_f32_e32 v146, v146, v182
	v_mul_f32_e32 v147, v147, v227
	v_mul_f32_e32 v147, v147, v183
	v_mul_f32_e32 v148, v148, v227
	v_mul_f32_e32 v148, v148, v184
	v_mul_f32_e32 v149, v149, v227
	v_mul_f32_e32 v149, v149, v185
	global_store_dwordx4 v163, v[118:121], s[100:101]
	global_store_dwordx4 v163, v[122:125], s[100:101] offset:16
	global_store_dwordx4 v163, v[126:129], s[100:101] offset:2048
	global_store_dwordx4 v163, v[130:133], s[100:101] offset:2064
	global_store_dwordx4 v194, v[134:137], s[100:101]
	global_store_dwordx4 v194, v[138:141], s[100:101] offset:16
	global_store_dwordx4 v194, v[142:145], s[100:101] offset:2048
	global_store_dwordx4 v194, v[146:149], s[100:101] offset:2064
	s_branch .LBB0_1307
